# v2: OUT stats atomics pre-reduced in LDS + INA rope table loads hoisted to one wait
# baseline (speedup 1.0000x reference)
.LBB0_304:
	s_lshl_b32 s100, s56, 6
	s_lshl_b32 s101, s54, 3
	s_add_i32 s100, s100, s101
	s_add_i32 s100, s100, 0x20200
	v_lshl_add_u32 v226, v181, 3, s100
	s_lshl_b32 s25, s75, 8
	v_mov_b32_e32 v148, v179
	v_mov_b32_e32 v149, v181
	s_or_b32 s25, s25, s56
	s_lshl_b32 s24, s76, 8
	v_lshl_add_u32 v146, v148, 3, s25
	v_readlane_b32 s42, v254, 35
	s_add_i32 s24, s24, s54
	v_ashrrev_i32_e32 v147, 31, v146
	v_readlane_b32 s43, v254, 36
	v_add_u32_e32 v196, s24, v149
	v_ashrrev_i32_e32 v197, 31, v196
	v_lshl_add_u64 v[62:63], v[146:147], 2, s[42:43]
	v_lshlrev_b64 v[146:147], 1, v[146:147]
	v_lshl_add_u64 v[194:195], s[28:29], 0, v[146:147]
	v_lshl_add_u64 v[192:193], s[30:31], 0, v[146:147]
	v_lshlrev_b32_e32 v146, 2, v149
	v_lshl_add_u32 v146, v148, 6, v146
	v_lshlrev_b64 v[210:211], 12, v[196:197]
	v_xor_b32_e32 v214, 64, v146
	v_lshl_add_u64 v[146:147], v[194:195], 0, v[210:211]
	global_load_dwordx4 v[66:69], v[62:63], off offset:16
	global_load_dwordx4 v[70:73], v[62:63], off
	global_load_dwordx4 v[58:61], v[62:63], off offset:528
	s_nop 0
	global_load_dwordx4 v[62:65], v[62:63], off offset:512
	s_nop 0
	global_load_dwordx4 v[174:177], v[146:147], off
	global_load_dwordx4 v[170:173], v[146:147], off offset:256
	v_add_u32_e32 v204, 16, v196
	v_ashrrev_i32_e32 v205, 31, v204
	v_add_u32_e32 v200, 32, v196
	v_lshlrev_b64 v[208:209], 12, v[204:205]
	v_ashrrev_i32_e32 v201, 31, v200
	v_add_u32_e32 v198, 48, v196
	v_lshl_add_u64 v[146:147], v[194:195], 0, v[208:209]
	v_lshlrev_b64 v[206:207], 12, v[200:201]
	v_ashrrev_i32_e32 v199, 31, v198
	global_load_dwordx4 v[166:169], v[146:147], off
	global_load_dwordx4 v[162:165], v[146:147], off offset:256
	v_lshl_add_u64 v[146:147], v[194:195], 0, v[206:207]
	v_lshlrev_b64 v[202:203], 12, v[198:199]
	global_load_dwordx4 v[158:161], v[146:147], off
	global_load_dwordx4 v[154:157], v[146:147], off offset:256
	v_lshl_add_u64 v[146:147], v[194:195], 0, v[202:203]
	v_cmp_eq_u32_e32 vcc, 0, v148
	global_load_dwordx4 v[150:153], v[146:147], off
	s_nop 0
	global_load_dwordx4 v[146:149], v[146:147], off offset:256
	v_lshl_add_u64 v[210:211], v[192:193], 0, v[210:211]
	s_waitcnt vmcnt(0)
	v_lshlrev_b32_e32 v218, 16, v174
	v_and_b32_e32 v219, 0xffff0000, v174
	v_lshlrev_b32_e32 v174, 16, v175
	v_and_b32_e32 v175, 0xffff0000, v175
	v_lshlrev_b32_e32 v216, 16, v176
	v_and_b32_e32 v217, 0xffff0000, v176
	v_lshlrev_b32_e32 v176, 16, v177
	v_and_b32_e32 v177, 0xffff0000, v177
	v_pk_fma_f32 v[144:145], v[174:175], s[16:17], v[144:145] op_sel_hi:[1,0,1]
	v_pk_fma_f32 v[142:143], v[218:219], s[16:17], v[142:143] op_sel_hi:[1,0,1]
	v_add_f32_e32 v175, v144, v145
	v_add_f32_e32 v174, v142, v143
	v_pk_fma_f32 v[140:141], v[176:177], s[16:17], v[140:141] op_sel_hi:[1,0,1]
	v_pk_fma_f32 v[138:139], v[216:217], s[16:17], v[138:139] op_sel_hi:[1,0,1]
	v_add_f32_e32 v174, v174, v175
	v_add_f32_e32 v176, v138, v139
	v_add_f32_e32 v177, v140, v141
	v_add_f32_e32 v174, 0, v174
	v_add_f32_e32 v176, v176, v177
	v_mul_f32_e32 v175, v143, v143
	v_mul_f32_e32 v215, v145, v145
	v_add_f32_e32 v176, v176, v174
	v_mul_f32_e32 v174, v139, v139
	v_mul_f32_e32 v177, v141, v141
	v_fmac_f32_e32 v175, v142, v142
	v_fmac_f32_e32 v215, v144, v144
	v_fmac_f32_e32 v174, v138, v138
	v_fmac_f32_e32 v177, v140, v140
	v_add_f32_e32 v175, v175, v215
	v_add_f32_e32 v174, v174, v177
	v_add_f32_e32 v177, v175, v174
	v_pk_mul_f32 v[144:145], v[72:73], v[144:145]
	v_pk_mul_f32 v[142:143], v[70:71], v[142:143]
	v_pk_mul_f32 v[174:175], v[68:69], v[140:141]
	v_pk_mul_f32 v[140:141], v[66:67], v[138:139]
	v_cvt_pk_bf16_f32 v138, v142, v143
	v_cvt_pk_bf16_f32 v139, v144, v145
	v_lshlrev_b32_e32 v142, 16, v170
	v_cvt_pk_bf16_f32 v140, v140, v141
	v_cvt_pk_bf16_f32 v141, v174, v175
	v_and_b32_e32 v143, 0xffff0000, v170
	v_lshlrev_b32_e32 v144, 16, v171
	v_and_b32_e32 v145, 0xffff0000, v171
	global_store_dwordx4 v[210:211], v[138:141], off
	v_pk_fma_f32 v[136:137], v[144:145], s[16:17], v[136:137] op_sel_hi:[1,0,1]
	v_pk_fma_f32 v[134:135], v[142:143], s[16:17], v[134:135] op_sel_hi:[1,0,1]
	v_lshlrev_b32_e32 v138, 16, v172
	v_and_b32_e32 v139, 0xffff0000, v172
	v_lshlrev_b32_e32 v140, 16, v173
	v_and_b32_e32 v141, 0xffff0000, v173
	v_add_f32_e32 v142, v134, v135
	v_add_f32_e32 v143, v136, v137
	v_pk_fma_f32 v[132:133], v[140:141], s[16:17], v[132:133] op_sel_hi:[1,0,1]
	v_pk_fma_f32 v[130:131], v[138:139], s[16:17], v[130:131] op_sel_hi:[1,0,1]
	v_add_f32_e32 v142, v142, v143
	v_add_f32_e32 v138, v130, v131
	v_add_f32_e32 v139, v132, v133
	v_add_f32_e32 v142, v142, v176
	v_mul_f32_e32 v143, v135, v135
	v_mul_f32_e32 v144, v137, v137
	v_add_f32_e32 v138, v138, v139
	v_fmac_f32_e32 v143, v134, v134
	v_fmac_f32_e32 v144, v136, v136
	v_add_f32_e32 v140, v138, v142
	v_mul_f32_e32 v138, v131, v131
	v_mul_f32_e32 v139, v133, v133
	v_add_f32_e32 v143, v143, v144
	v_fmac_f32_e32 v138, v130, v130
	v_fmac_f32_e32 v139, v132, v132
	v_add_f32_e32 v143, v177, v143
	v_add_f32_e32 v138, v138, v139
	v_add_f32_e32 v141, v138, v143
	v_pk_mul_f32 v[136:137], v[64:65], v[136:137]
	v_pk_mul_f32 v[134:135], v[62:63], v[134:135]
	v_pk_mul_f32 v[138:139], v[60:61], v[132:133]
	v_pk_mul_f32 v[132:133], v[58:59], v[130:131]
	v_cvt_pk_bf16_f32 v130, v134, v135
	v_cvt_pk_bf16_f32 v131, v136, v137
	s_nop 0
	v_cvt_pk_bf16_f32 v132, v132, v133
	v_cvt_pk_bf16_f32 v133, v138, v139
	global_store_dwordx4 v[210:211], v[130:133], off offset:256
	ds_bpermute_b32 v130, v214, v140
	ds_bpermute_b32 v131, v214, v141
	s_waitcnt lgkmcnt(1)
	v_add_f32_e32 v130, v140, v130
	s_waitcnt lgkmcnt(0)
	v_add_f32_e32 v131, v141, v131
	v_mov_b32_e32 v132, v130
	v_mov_b32_e32 v133, v131
	s_nop 0
	v_permlane32_swap_b32_e32 v130, v132
	v_permlane32_swap_b32_e32 v131, v133
	s_and_saveexec_b64 s[24:25], vcc
	s_cbranch_execz .LBB0_306
	v_add_f32_e32 v130, v130, v132
	v_add_f32_e32 v131, v131, v133
	ds_write_b64 v226, v[130:131]
.LBB0_306:
	s_or_b64 exec, exec, s[24:25]
	v_lshlrev_b32_e32 v136, 16, v166
	v_and_b32_e32 v137, 0xffff0000, v166
	v_lshlrev_b32_e32 v138, 16, v167
	v_and_b32_e32 v139, 0xffff0000, v167
	v_lshlrev_b32_e32 v132, 16, v168
	v_and_b32_e32 v133, 0xffff0000, v168
	v_lshlrev_b32_e32 v134, 16, v169
	v_and_b32_e32 v135, 0xffff0000, v169
	v_pk_fma_f32 v[128:129], v[138:139], s[16:17], v[128:129] op_sel_hi:[1,0,1]
	v_pk_fma_f32 v[126:127], v[136:137], s[16:17], v[126:127] op_sel_hi:[1,0,1]
	v_add_f32_e32 v137, v128, v129
	v_add_f32_e32 v136, v126, v127
	v_pk_fma_f32 v[124:125], v[134:135], s[16:17], v[124:125] op_sel_hi:[1,0,1]
	v_pk_fma_f32 v[122:123], v[132:133], s[16:17], v[122:123] op_sel_hi:[1,0,1]
	v_add_f32_e32 v136, v136, v137
	v_add_f32_e32 v132, v122, v123
	v_add_f32_e32 v133, v124, v125
	v_add_f32_e32 v136, 0, v136
	v_add_f32_e32 v132, v132, v133
	v_mul_f32_e32 v137, v127, v127
	v_mul_f32_e32 v138, v129, v129
	v_add_f32_e32 v134, v132, v136
	v_mul_f32_e32 v132, v123, v123
	v_mul_f32_e32 v133, v125, v125
	v_fmac_f32_e32 v137, v126, v126
	v_fmac_f32_e32 v138, v128, v128
	v_fmac_f32_e32 v132, v122, v122
	v_fmac_f32_e32 v133, v124, v124
	v_add_f32_e32 v137, v137, v138
	v_add_f32_e32 v132, v132, v133
	v_add_f32_e32 v135, v137, v132
	v_pk_mul_f32 v[128:129], v[72:73], v[128:129]
	v_pk_mul_f32 v[126:127], v[70:71], v[126:127]
	v_pk_mul_f32 v[132:133], v[68:69], v[124:125]
	v_pk_mul_f32 v[124:125], v[66:67], v[122:123]
	v_lshl_add_u64 v[130:131], v[192:193], 0, v[208:209]
	v_cvt_pk_bf16_f32 v122, v126, v127
	v_cvt_pk_bf16_f32 v123, v128, v129
	v_cvt_pk_bf16_f32 v124, v124, v125
	v_cvt_pk_bf16_f32 v125, v132, v133
	v_lshlrev_b32_e32 v126, 16, v162
	v_and_b32_e32 v127, 0xffff0000, v162
	v_lshlrev_b32_e32 v128, 16, v163
	v_and_b32_e32 v129, 0xffff0000, v163
	global_store_dwordx4 v[130:131], v[122:125], off
	v_pk_fma_f32 v[120:121], v[128:129], s[16:17], v[120:121] op_sel_hi:[1,0,1]
	v_pk_fma_f32 v[118:119], v[126:127], s[16:17], v[118:119] op_sel_hi:[1,0,1]
	v_lshlrev_b32_e32 v122, 16, v164
	v_and_b32_e32 v123, 0xffff0000, v164
	v_lshlrev_b32_e32 v124, 16, v165
	v_and_b32_e32 v125, 0xffff0000, v165
	v_add_f32_e32 v126, v118, v119
	v_add_f32_e32 v127, v120, v121
	v_pk_fma_f32 v[116:117], v[124:125], s[16:17], v[116:117] op_sel_hi:[1,0,1]
	v_pk_fma_f32 v[114:115], v[122:123], s[16:17], v[114:115] op_sel_hi:[1,0,1]
	v_add_f32_e32 v126, v126, v127
	v_add_f32_e32 v122, v114, v115
	v_add_f32_e32 v123, v116, v117
	v_add_f32_e32 v126, v126, v134
	v_mul_f32_e32 v127, v119, v119
	v_mul_f32_e32 v128, v121, v121
	v_add_f32_e32 v122, v122, v123
	v_fmac_f32_e32 v127, v118, v118
	v_fmac_f32_e32 v128, v120, v120
	v_add_f32_e32 v124, v122, v126
	v_mul_f32_e32 v122, v115, v115
	v_mul_f32_e32 v123, v117, v117
	v_add_f32_e32 v127, v127, v128
	v_fmac_f32_e32 v122, v114, v114
	v_fmac_f32_e32 v123, v116, v116
	v_add_f32_e32 v127, v135, v127
	v_add_f32_e32 v122, v122, v123
	v_add_f32_e32 v125, v122, v127
	v_pk_mul_f32 v[118:119], v[62:63], v[118:119]
	v_pk_mul_f32 v[122:123], v[60:61], v[116:117]
	v_pk_mul_f32 v[116:117], v[58:59], v[114:115]
	v_cvt_pk_bf16_f32 v114, v118, v119
	ds_bpermute_b32 v118, v214, v124
	ds_bpermute_b32 v119, v214, v125
	v_pk_mul_f32 v[120:121], v[64:65], v[120:121]
	s_nop 0
	v_cvt_pk_bf16_f32 v115, v120, v121
	v_cvt_pk_bf16_f32 v116, v116, v117
	v_cvt_pk_bf16_f32 v117, v122, v123
	global_store_dwordx4 v[130:131], v[114:117], off offset:256
	s_waitcnt lgkmcnt(1)
	s_nop 0
	v_add_f32_e32 v114, v124, v118
	s_waitcnt lgkmcnt(0)
	v_add_f32_e32 v115, v125, v119
	v_mov_b32_e32 v116, v114
	v_mov_b32_e32 v117, v115
	s_nop 0
	v_permlane32_swap_b32_e32 v114, v116
	v_permlane32_swap_b32_e32 v115, v117
	s_and_saveexec_b64 s[24:25], vcc
	s_cbranch_execz .LBB0_308
	v_add_f32_e32 v114, v114, v116
	v_add_f32_e32 v115, v115, v117
	ds_write_b64 v226, v[114:115] offset:128
.LBB0_308:
	s_or_b64 exec, exec, s[24:25]
	v_lshlrev_b32_e32 v120, 16, v158
	v_and_b32_e32 v121, 0xffff0000, v158
	v_lshlrev_b32_e32 v122, 16, v159
	v_and_b32_e32 v123, 0xffff0000, v159
	v_lshlrev_b32_e32 v116, 16, v160
	v_and_b32_e32 v117, 0xffff0000, v160
	v_lshlrev_b32_e32 v118, 16, v161
	v_and_b32_e32 v119, 0xffff0000, v161
	v_pk_fma_f32 v[112:113], v[122:123], s[16:17], v[112:113] op_sel_hi:[1,0,1]
	v_pk_fma_f32 v[110:111], v[120:121], s[16:17], v[110:111] op_sel_hi:[1,0,1]
	v_add_f32_e32 v121, v112, v113
	v_add_f32_e32 v120, v110, v111
	v_pk_fma_f32 v[108:109], v[118:119], s[16:17], v[108:109] op_sel_hi:[1,0,1]
	v_pk_fma_f32 v[106:107], v[116:117], s[16:17], v[106:107] op_sel_hi:[1,0,1]
	v_add_f32_e32 v120, v120, v121
	v_add_f32_e32 v116, v106, v107
	v_add_f32_e32 v117, v108, v109
	v_add_f32_e32 v120, 0, v120
	v_add_f32_e32 v116, v116, v117
	v_mul_f32_e32 v121, v111, v111
	v_mul_f32_e32 v122, v113, v113
	v_add_f32_e32 v118, v116, v120
	v_mul_f32_e32 v116, v107, v107
	v_mul_f32_e32 v117, v109, v109
	v_fmac_f32_e32 v121, v110, v110
	v_fmac_f32_e32 v122, v112, v112
	v_fmac_f32_e32 v116, v106, v106
	v_fmac_f32_e32 v117, v108, v108
	v_add_f32_e32 v121, v121, v122
	v_add_f32_e32 v116, v116, v117
	v_add_f32_e32 v119, v121, v116
	v_pk_mul_f32 v[112:113], v[72:73], v[112:113]
	v_pk_mul_f32 v[110:111], v[70:71], v[110:111]
	v_pk_mul_f32 v[116:117], v[68:69], v[108:109]
	v_pk_mul_f32 v[108:109], v[66:67], v[106:107]
	v_lshl_add_u64 v[114:115], v[192:193], 0, v[206:207]
	v_cvt_pk_bf16_f32 v106, v110, v111
	v_cvt_pk_bf16_f32 v107, v112, v113
	v_cvt_pk_bf16_f32 v108, v108, v109
	v_cvt_pk_bf16_f32 v109, v116, v117
	v_lshlrev_b32_e32 v110, 16, v154
	v_and_b32_e32 v111, 0xffff0000, v154
	v_lshlrev_b32_e32 v112, 16, v155
	v_and_b32_e32 v113, 0xffff0000, v155
	global_store_dwordx4 v[114:115], v[106:109], off
	v_pk_fma_f32 v[104:105], v[112:113], s[16:17], v[104:105] op_sel_hi:[1,0,1]
	v_pk_fma_f32 v[102:103], v[110:111], s[16:17], v[102:103] op_sel_hi:[1,0,1]
	v_lshlrev_b32_e32 v106, 16, v156
	v_and_b32_e32 v107, 0xffff0000, v156
	v_lshlrev_b32_e32 v108, 16, v157
	v_and_b32_e32 v109, 0xffff0000, v157
	v_add_f32_e32 v110, v102, v103
	v_add_f32_e32 v111, v104, v105
	v_pk_fma_f32 v[100:101], v[108:109], s[16:17], v[100:101] op_sel_hi:[1,0,1]
	v_pk_fma_f32 v[98:99], v[106:107], s[16:17], v[98:99] op_sel_hi:[1,0,1]
	v_add_f32_e32 v110, v110, v111
	v_add_f32_e32 v106, v98, v99
	v_add_f32_e32 v107, v100, v101
	v_add_f32_e32 v110, v110, v118
	v_mul_f32_e32 v111, v103, v103
	v_mul_f32_e32 v112, v105, v105
	v_add_f32_e32 v106, v106, v107
	v_fmac_f32_e32 v111, v102, v102
	v_fmac_f32_e32 v112, v104, v104
	v_add_f32_e32 v108, v106, v110
	v_mul_f32_e32 v106, v99, v99
	v_mul_f32_e32 v107, v101, v101
	v_add_f32_e32 v111, v111, v112
	v_fmac_f32_e32 v106, v98, v98
	v_fmac_f32_e32 v107, v100, v100
	v_add_f32_e32 v111, v119, v111
	v_add_f32_e32 v106, v106, v107
	v_add_f32_e32 v109, v106, v111
	v_pk_mul_f32 v[102:103], v[62:63], v[102:103]
	v_pk_mul_f32 v[106:107], v[60:61], v[100:101]
	v_pk_mul_f32 v[100:101], v[58:59], v[98:99]
	v_cvt_pk_bf16_f32 v98, v102, v103
	ds_bpermute_b32 v102, v214, v108
	ds_bpermute_b32 v103, v214, v109
	v_pk_mul_f32 v[104:105], v[64:65], v[104:105]
	s_nop 0
	v_cvt_pk_bf16_f32 v99, v104, v105
	v_cvt_pk_bf16_f32 v100, v100, v101
	v_cvt_pk_bf16_f32 v101, v106, v107
	global_store_dwordx4 v[114:115], v[98:101], off offset:256
	s_waitcnt lgkmcnt(1)
	s_nop 0
	v_add_f32_e32 v98, v108, v102
	s_waitcnt lgkmcnt(0)
	v_add_f32_e32 v99, v109, v103
	v_mov_b32_e32 v100, v98
	v_mov_b32_e32 v101, v99
	s_nop 0
	v_permlane32_swap_b32_e32 v98, v100
	v_permlane32_swap_b32_e32 v99, v101
	s_and_saveexec_b64 s[24:25], vcc
	s_mov_b64 s[96:97], s[62:63]
	s_cbranch_execz .LBB0_310
	v_add_f32_e32 v98, v98, v100
	v_add_f32_e32 v99, v99, v101
	ds_write_b64 v226, v[98:99] offset:256
.LBB0_310:
	s_or_b64 exec, exec, s[24:25]
	v_lshlrev_b32_e32 v104, 16, v150
	v_and_b32_e32 v105, 0xffff0000, v150
	v_lshlrev_b32_e32 v106, 16, v151
	v_and_b32_e32 v107, 0xffff0000, v151
	v_lshlrev_b32_e32 v100, 16, v152
	v_and_b32_e32 v101, 0xffff0000, v152
	v_lshlrev_b32_e32 v102, 16, v153
	v_and_b32_e32 v103, 0xffff0000, v153
	v_pk_fma_f32 v[96:97], v[106:107], s[16:17], v[96:97] op_sel_hi:[1,0,1]
	v_pk_fma_f32 v[94:95], v[104:105], s[16:17], v[94:95] op_sel_hi:[1,0,1]
	v_add_f32_e32 v105, v96, v97
	v_add_f32_e32 v104, v94, v95
	v_pk_fma_f32 v[92:93], v[102:103], s[16:17], v[92:93] op_sel_hi:[1,0,1]
	v_pk_fma_f32 v[90:91], v[100:101], s[16:17], v[90:91] op_sel_hi:[1,0,1]
	v_add_f32_e32 v104, v104, v105
	v_add_f32_e32 v100, v90, v91
	v_add_f32_e32 v101, v92, v93
	v_add_f32_e32 v104, 0, v104
	v_add_f32_e32 v100, v100, v101
	v_mul_f32_e32 v105, v95, v95
	v_mul_f32_e32 v106, v97, v97
	v_add_f32_e32 v102, v100, v104
	v_mul_f32_e32 v100, v91, v91
	v_mul_f32_e32 v101, v93, v93
	v_fmac_f32_e32 v105, v94, v94
	v_fmac_f32_e32 v106, v96, v96
	v_fmac_f32_e32 v100, v90, v90
	v_fmac_f32_e32 v101, v92, v92
	v_add_f32_e32 v105, v105, v106
	v_add_f32_e32 v100, v100, v101
	v_add_f32_e32 v103, v105, v100
	v_pk_mul_f32 v[96:97], v[72:73], v[96:97]
	v_pk_mul_f32 v[94:95], v[70:71], v[94:95]
	v_pk_mul_f32 v[100:101], v[68:69], v[92:93]
	v_pk_mul_f32 v[92:93], v[66:67], v[90:91]
	v_lshl_add_u64 v[98:99], v[192:193], 0, v[202:203]
	v_cvt_pk_bf16_f32 v90, v94, v95
	v_cvt_pk_bf16_f32 v91, v96, v97
	v_cvt_pk_bf16_f32 v92, v92, v93
	v_cvt_pk_bf16_f32 v93, v100, v101
	v_lshlrev_b32_e32 v94, 16, v146
	v_and_b32_e32 v95, 0xffff0000, v146
	v_lshlrev_b32_e32 v96, 16, v147
	v_and_b32_e32 v97, 0xffff0000, v147
	global_store_dwordx4 v[98:99], v[90:93], off
	v_pk_fma_f32 v[88:89], v[96:97], s[16:17], v[88:89] op_sel_hi:[1,0,1]
	v_pk_fma_f32 v[86:87], v[94:95], s[16:17], v[86:87] op_sel_hi:[1,0,1]
	v_lshlrev_b32_e32 v90, 16, v148
	v_and_b32_e32 v91, 0xffff0000, v148
	v_lshlrev_b32_e32 v92, 16, v149
	v_and_b32_e32 v93, 0xffff0000, v149
	v_add_f32_e32 v94, v86, v87
	v_add_f32_e32 v95, v88, v89
	v_pk_fma_f32 v[84:85], v[92:93], s[16:17], v[84:85] op_sel_hi:[1,0,1]
	v_pk_fma_f32 v[82:83], v[90:91], s[16:17], v[82:83] op_sel_hi:[1,0,1]
	v_add_f32_e32 v94, v94, v95
	v_add_f32_e32 v90, v82, v83
	v_add_f32_e32 v91, v84, v85
	v_add_f32_e32 v94, v94, v102
	v_mul_f32_e32 v95, v87, v87
	v_mul_f32_e32 v96, v89, v89
	v_add_f32_e32 v90, v90, v91
	v_fmac_f32_e32 v95, v86, v86
	v_fmac_f32_e32 v96, v88, v88
	v_add_f32_e32 v92, v90, v94
	v_mul_f32_e32 v90, v83, v83
	v_mul_f32_e32 v91, v85, v85
	v_add_f32_e32 v95, v95, v96
	v_fmac_f32_e32 v90, v82, v82
	v_fmac_f32_e32 v91, v84, v84
	v_add_f32_e32 v95, v103, v95
	v_add_f32_e32 v90, v90, v91
	v_add_f32_e32 v93, v90, v95
	v_pk_mul_f32 v[86:87], v[62:63], v[86:87]
	v_pk_mul_f32 v[90:91], v[60:61], v[84:85]
	v_pk_mul_f32 v[84:85], v[58:59], v[82:83]
	v_cvt_pk_bf16_f32 v82, v86, v87
	ds_bpermute_b32 v86, v214, v92
	ds_bpermute_b32 v87, v214, v93
	v_pk_mul_f32 v[88:89], v[64:65], v[88:89]
	s_nop 0
	v_cvt_pk_bf16_f32 v83, v88, v89
	v_cvt_pk_bf16_f32 v84, v84, v85
	v_cvt_pk_bf16_f32 v85, v90, v91
	global_store_dwordx4 v[98:99], v[82:85], off offset:256
	s_waitcnt lgkmcnt(1)
	s_nop 0
	v_add_f32_e32 v82, v92, v86
	s_waitcnt lgkmcnt(0)
	v_add_f32_e32 v83, v93, v87
	v_mov_b32_e32 v84, v82
	v_mov_b32_e32 v85, v83
	s_nop 0
	v_permlane32_swap_b32_e32 v82, v84
	v_permlane32_swap_b32_e32 v83, v85
	s_and_saveexec_b64 s[24:25], vcc
	s_cbranch_execz .LBB0_312
	v_add_f32_e32 v82, v82, v84
	v_add_f32_e32 v83, v83, v85
	ds_write_b64 v226, v[82:83] offset:384
.LBB0_312:
	s_or_b64 exec, exec, s[24:25]
	v_add_u32_e32 v120, 0x80, v196
	v_ashrrev_i32_e32 v121, 31, v120
	v_lshlrev_b64 v[124:125], 12, v[120:121]
	v_lshl_add_u64 v[82:83], v[194:195], 0, v[124:125]
	global_load_dwordx4 v[126:129], v[82:83], off
	global_load_dwordx4 v[106:109], v[82:83], off offset:256
	v_add_u32_e32 v116, 0x90, v196
	v_ashrrev_i32_e32 v117, 31, v116
	v_add_u32_e32 v112, 0xa0, v196
	v_lshlrev_b64 v[122:123], 12, v[116:117]
	v_ashrrev_i32_e32 v113, 31, v112
	v_add_u32_e32 v110, 0xb0, v196
	v_lshl_add_u64 v[82:83], v[194:195], 0, v[122:123]
	v_lshlrev_b64 v[118:119], 12, v[112:113]
	v_ashrrev_i32_e32 v111, 31, v110
	global_load_dwordx4 v[102:105], v[82:83], off
	global_load_dwordx4 v[98:101], v[82:83], off offset:256
	v_lshl_add_u64 v[82:83], v[194:195], 0, v[118:119]
	v_lshlrev_b64 v[114:115], 12, v[110:111]
	global_load_dwordx4 v[94:97], v[82:83], off
	global_load_dwordx4 v[90:93], v[82:83], off offset:256
	v_lshl_add_u64 v[82:83], v[194:195], 0, v[114:115]
	global_load_dwordx4 v[86:89], v[82:83], off
	s_nop 0
	global_load_dwordx4 v[82:85], v[82:83], off offset:256
	v_lshl_add_u64 v[124:125], v[192:193], 0, v[124:125]
	s_waitcnt vmcnt(7)
	v_lshlrev_b32_e32 v132, 16, v126
	v_and_b32_e32 v133, 0xffff0000, v126
	v_lshlrev_b32_e32 v126, 16, v127
	v_and_b32_e32 v127, 0xffff0000, v127
	v_lshlrev_b32_e32 v130, 16, v128
	v_and_b32_e32 v131, 0xffff0000, v128
	v_lshlrev_b32_e32 v128, 16, v129
	v_and_b32_e32 v129, 0xffff0000, v129
	v_pk_fma_f32 v[80:81], v[126:127], s[16:17], v[80:81] op_sel_hi:[1,0,1]
	v_pk_fma_f32 v[78:79], v[132:133], s[16:17], v[78:79] op_sel_hi:[1,0,1]
	v_add_f32_e32 v127, v80, v81
	v_add_f32_e32 v126, v78, v79
	v_pk_fma_f32 v[76:77], v[128:129], s[16:17], v[76:77] op_sel_hi:[1,0,1]
	v_pk_fma_f32 v[74:75], v[130:131], s[16:17], v[74:75] op_sel_hi:[1,0,1]
	v_add_f32_e32 v126, v126, v127
	v_add_f32_e32 v128, v74, v75
	v_add_f32_e32 v129, v76, v77
	v_add_f32_e32 v126, 0, v126
	v_add_f32_e32 v128, v128, v129
	v_mul_f32_e32 v127, v79, v79
	v_mul_f32_e32 v132, v81, v81
	v_add_f32_e32 v128, v128, v126
	v_mul_f32_e32 v126, v75, v75
	v_mul_f32_e32 v129, v77, v77
	v_fmac_f32_e32 v127, v78, v78
	v_fmac_f32_e32 v132, v80, v80
	v_fmac_f32_e32 v126, v74, v74
	v_fmac_f32_e32 v129, v76, v76
	v_add_f32_e32 v127, v127, v132
	v_add_f32_e32 v126, v126, v129
	v_add_f32_e32 v129, v127, v126
	v_pk_mul_f32 v[80:81], v[72:73], v[80:81]
	v_pk_mul_f32 v[78:79], v[70:71], v[78:79]
	v_pk_mul_f32 v[126:127], v[68:69], v[76:77]
	v_pk_mul_f32 v[76:77], v[66:67], v[74:75]
	v_cvt_pk_bf16_f32 v74, v78, v79
	v_cvt_pk_bf16_f32 v75, v80, v81
	s_waitcnt vmcnt(6)
	v_lshlrev_b32_e32 v78, 16, v106
	v_cvt_pk_bf16_f32 v76, v76, v77
	v_cvt_pk_bf16_f32 v77, v126, v127
	v_and_b32_e32 v79, 0xffff0000, v106
	v_lshlrev_b32_e32 v80, 16, v107
	v_and_b32_e32 v81, 0xffff0000, v107
	global_store_dwordx4 v[124:125], v[74:77], off
	v_pk_fma_f32 v[56:57], v[80:81], s[16:17], v[56:57] op_sel_hi:[1,0,1]
	v_pk_fma_f32 v[54:55], v[78:79], s[16:17], v[54:55] op_sel_hi:[1,0,1]
	v_lshlrev_b32_e32 v74, 16, v108
	v_and_b32_e32 v75, 0xffff0000, v108
	v_lshlrev_b32_e32 v76, 16, v109
	v_and_b32_e32 v77, 0xffff0000, v109
	v_add_f32_e32 v78, v54, v55
	v_add_f32_e32 v79, v56, v57
	v_pk_fma_f32 v[52:53], v[76:77], s[16:17], v[52:53] op_sel_hi:[1,0,1]
	v_pk_fma_f32 v[50:51], v[74:75], s[16:17], v[50:51] op_sel_hi:[1,0,1]
	v_add_f32_e32 v78, v78, v79
	v_add_f32_e32 v74, v50, v51
	v_add_f32_e32 v75, v52, v53
	v_add_f32_e32 v78, v78, v128
	v_mul_f32_e32 v79, v55, v55
	v_mul_f32_e32 v80, v57, v57
	v_add_f32_e32 v74, v74, v75
	v_fmac_f32_e32 v79, v54, v54
	v_fmac_f32_e32 v80, v56, v56
	v_add_f32_e32 v76, v74, v78
	v_mul_f32_e32 v74, v51, v51
	v_mul_f32_e32 v75, v53, v53
	v_add_f32_e32 v79, v79, v80
	v_fmac_f32_e32 v74, v50, v50
	v_fmac_f32_e32 v75, v52, v52
	v_add_f32_e32 v79, v129, v79
	v_add_f32_e32 v74, v74, v75
	v_add_f32_e32 v77, v74, v79
	v_pk_mul_f32 v[56:57], v[64:65], v[56:57]
	v_pk_mul_f32 v[54:55], v[62:63], v[54:55]
	v_pk_mul_f32 v[74:75], v[60:61], v[52:53]
	v_pk_mul_f32 v[52:53], v[58:59], v[50:51]
	v_cvt_pk_bf16_f32 v50, v54, v55
	v_cvt_pk_bf16_f32 v51, v56, v57
	s_nop 0
	v_cvt_pk_bf16_f32 v52, v52, v53
	v_cvt_pk_bf16_f32 v53, v74, v75
	global_store_dwordx4 v[124:125], v[50:53], off offset:256
	ds_bpermute_b32 v50, v214, v76
	ds_bpermute_b32 v51, v214, v77
	s_waitcnt lgkmcnt(1)
	v_add_f32_e32 v50, v76, v50
	s_waitcnt lgkmcnt(0)
	v_add_f32_e32 v51, v77, v51
	v_mov_b32_e32 v52, v50
	v_mov_b32_e32 v53, v51
	s_nop 0
	v_permlane32_swap_b32_e32 v50, v52
	v_permlane32_swap_b32_e32 v51, v53
	s_and_saveexec_b64 s[24:25], vcc
	s_cbranch_execz .LBB0_314
	v_add_f32_e32 v50, v50, v52
	v_add_f32_e32 v51, v51, v53
	ds_write_b64 v226, v[50:51] offset:1024
.LBB0_314:
	s_or_b64 exec, exec, s[24:25]
	s_waitcnt vmcnt(7)
	v_lshlrev_b32_e32 v56, 16, v102
	v_and_b32_e32 v57, 0xffff0000, v102
	v_lshlrev_b32_e32 v74, 16, v103
	v_and_b32_e32 v75, 0xffff0000, v103
	v_lshlrev_b32_e32 v52, 16, v104
	v_and_b32_e32 v53, 0xffff0000, v104
	v_lshlrev_b32_e32 v54, 16, v105
	v_and_b32_e32 v55, 0xffff0000, v105
	v_pk_fma_f32 v[48:49], v[74:75], s[16:17], v[48:49] op_sel_hi:[1,0,1]
	v_pk_fma_f32 v[46:47], v[56:57], s[16:17], v[46:47] op_sel_hi:[1,0,1]
	v_add_f32_e32 v57, v48, v49
	v_add_f32_e32 v56, v46, v47
	v_pk_fma_f32 v[44:45], v[54:55], s[16:17], v[44:45] op_sel_hi:[1,0,1]
	v_pk_fma_f32 v[42:43], v[52:53], s[16:17], v[42:43] op_sel_hi:[1,0,1]
	v_add_f32_e32 v56, v56, v57
	v_add_f32_e32 v52, v42, v43
	v_add_f32_e32 v53, v44, v45
	v_add_f32_e32 v56, 0, v56
	v_add_f32_e32 v52, v52, v53
	v_mul_f32_e32 v57, v47, v47
	v_mul_f32_e32 v74, v49, v49
	v_add_f32_e32 v54, v52, v56
	v_mul_f32_e32 v52, v43, v43
	v_mul_f32_e32 v53, v45, v45
	v_fmac_f32_e32 v57, v46, v46
	v_fmac_f32_e32 v74, v48, v48
	v_fmac_f32_e32 v52, v42, v42
	v_fmac_f32_e32 v53, v44, v44
	v_add_f32_e32 v57, v57, v74
	v_add_f32_e32 v52, v52, v53
	v_add_f32_e32 v55, v57, v52
	v_pk_mul_f32 v[48:49], v[72:73], v[48:49]
	v_pk_mul_f32 v[46:47], v[70:71], v[46:47]
	v_pk_mul_f32 v[52:53], v[68:69], v[44:45]
	v_pk_mul_f32 v[44:45], v[66:67], v[42:43]
	v_lshl_add_u64 v[50:51], v[192:193], 0, v[122:123]
	v_cvt_pk_bf16_f32 v42, v46, v47
	v_cvt_pk_bf16_f32 v43, v48, v49
	v_cvt_pk_bf16_f32 v44, v44, v45
	v_cvt_pk_bf16_f32 v45, v52, v53
	s_waitcnt vmcnt(6)
	v_lshlrev_b32_e32 v46, 16, v98
	v_and_b32_e32 v47, 0xffff0000, v98
	v_lshlrev_b32_e32 v48, 16, v99
	v_and_b32_e32 v49, 0xffff0000, v99
	global_store_dwordx4 v[50:51], v[42:45], off
	v_pk_fma_f32 v[40:41], v[48:49], s[16:17], v[40:41] op_sel_hi:[1,0,1]
	v_pk_fma_f32 v[38:39], v[46:47], s[16:17], v[38:39] op_sel_hi:[1,0,1]
	v_lshlrev_b32_e32 v42, 16, v100
	v_and_b32_e32 v43, 0xffff0000, v100
	v_lshlrev_b32_e32 v44, 16, v101
	v_and_b32_e32 v45, 0xffff0000, v101
	v_add_f32_e32 v46, v38, v39
	v_add_f32_e32 v47, v40, v41
	v_pk_fma_f32 v[36:37], v[44:45], s[16:17], v[36:37] op_sel_hi:[1,0,1]
	v_pk_fma_f32 v[34:35], v[42:43], s[16:17], v[34:35] op_sel_hi:[1,0,1]
	v_add_f32_e32 v46, v46, v47
	v_add_f32_e32 v42, v34, v35
	v_add_f32_e32 v43, v36, v37
	v_add_f32_e32 v46, v46, v54
	v_mul_f32_e32 v47, v39, v39
	v_mul_f32_e32 v48, v41, v41
	v_add_f32_e32 v42, v42, v43
	v_fmac_f32_e32 v47, v38, v38
	v_fmac_f32_e32 v48, v40, v40
	v_add_f32_e32 v44, v42, v46
	v_mul_f32_e32 v42, v35, v35
	v_mul_f32_e32 v43, v37, v37
	v_add_f32_e32 v47, v47, v48
	v_fmac_f32_e32 v42, v34, v34
	v_fmac_f32_e32 v43, v36, v36
	v_add_f32_e32 v47, v55, v47
	v_add_f32_e32 v42, v42, v43
	v_add_f32_e32 v45, v42, v47
	v_pk_mul_f32 v[38:39], v[62:63], v[38:39]
	v_pk_mul_f32 v[42:43], v[60:61], v[36:37]
	v_pk_mul_f32 v[36:37], v[58:59], v[34:35]
	v_cvt_pk_bf16_f32 v34, v38, v39
	ds_bpermute_b32 v38, v214, v44
	ds_bpermute_b32 v39, v214, v45
	v_pk_mul_f32 v[40:41], v[64:65], v[40:41]
	s_nop 0
	v_cvt_pk_bf16_f32 v35, v40, v41
	v_cvt_pk_bf16_f32 v36, v36, v37
	v_cvt_pk_bf16_f32 v37, v42, v43
	global_store_dwordx4 v[50:51], v[34:37], off offset:256
	s_waitcnt lgkmcnt(1)
	s_nop 0
	v_add_f32_e32 v34, v44, v38
	s_waitcnt lgkmcnt(0)
	v_add_f32_e32 v35, v45, v39
	v_mov_b32_e32 v36, v34
	v_mov_b32_e32 v37, v35
	s_nop 0
	v_permlane32_swap_b32_e32 v34, v36
	v_permlane32_swap_b32_e32 v35, v37
	s_and_saveexec_b64 s[24:25], vcc
	s_cbranch_execz .LBB0_316
	v_add_f32_e32 v34, v34, v36
	v_add_f32_e32 v35, v35, v37
	ds_write_b64 v226, v[34:35] offset:1152
.LBB0_316:
	s_or_b64 exec, exec, s[24:25]
	s_waitcnt vmcnt(7)
	v_lshlrev_b32_e32 v40, 16, v94
	v_and_b32_e32 v41, 0xffff0000, v94
	v_lshlrev_b32_e32 v42, 16, v95
	v_and_b32_e32 v43, 0xffff0000, v95
	v_lshlrev_b32_e32 v36, 16, v96
	v_and_b32_e32 v37, 0xffff0000, v96
	v_lshlrev_b32_e32 v38, 16, v97
	v_and_b32_e32 v39, 0xffff0000, v97
	v_pk_fma_f32 v[32:33], v[42:43], s[16:17], v[32:33] op_sel_hi:[1,0,1]
	v_pk_fma_f32 v[30:31], v[40:41], s[16:17], v[30:31] op_sel_hi:[1,0,1]
	v_add_f32_e32 v41, v32, v33
	v_add_f32_e32 v40, v30, v31
	v_pk_fma_f32 v[28:29], v[38:39], s[16:17], v[28:29] op_sel_hi:[1,0,1]
	v_pk_fma_f32 v[26:27], v[36:37], s[16:17], v[26:27] op_sel_hi:[1,0,1]
	v_add_f32_e32 v40, v40, v41
	v_add_f32_e32 v36, v26, v27
	v_add_f32_e32 v37, v28, v29
	v_add_f32_e32 v40, 0, v40
	v_add_f32_e32 v36, v36, v37
	v_mul_f32_e32 v41, v31, v31
	v_mul_f32_e32 v42, v33, v33
	v_add_f32_e32 v38, v36, v40
	v_mul_f32_e32 v36, v27, v27
	v_mul_f32_e32 v37, v29, v29
	v_fmac_f32_e32 v41, v30, v30
	v_fmac_f32_e32 v42, v32, v32
	v_fmac_f32_e32 v36, v26, v26
	v_fmac_f32_e32 v37, v28, v28
	v_add_f32_e32 v41, v41, v42
	v_add_f32_e32 v36, v36, v37
	v_add_f32_e32 v39, v41, v36
	v_pk_mul_f32 v[32:33], v[72:73], v[32:33]
	v_pk_mul_f32 v[30:31], v[70:71], v[30:31]
	v_pk_mul_f32 v[36:37], v[68:69], v[28:29]
	v_pk_mul_f32 v[28:29], v[66:67], v[26:27]
	v_lshl_add_u64 v[34:35], v[192:193], 0, v[118:119]
	v_cvt_pk_bf16_f32 v26, v30, v31
	v_cvt_pk_bf16_f32 v27, v32, v33
	v_cvt_pk_bf16_f32 v28, v28, v29
	v_cvt_pk_bf16_f32 v29, v36, v37
	s_waitcnt vmcnt(6)
	v_lshlrev_b32_e32 v30, 16, v90
	v_and_b32_e32 v31, 0xffff0000, v90
	v_lshlrev_b32_e32 v32, 16, v91
	v_and_b32_e32 v33, 0xffff0000, v91
	global_store_dwordx4 v[34:35], v[26:29], off
	v_pk_fma_f32 v[24:25], v[32:33], s[16:17], v[24:25] op_sel_hi:[1,0,1]
	v_pk_fma_f32 v[22:23], v[30:31], s[16:17], v[22:23] op_sel_hi:[1,0,1]
	v_lshlrev_b32_e32 v26, 16, v92
	v_and_b32_e32 v27, 0xffff0000, v92
	v_lshlrev_b32_e32 v28, 16, v93
	v_and_b32_e32 v29, 0xffff0000, v93
	v_add_f32_e32 v30, v22, v23
	v_add_f32_e32 v31, v24, v25
	v_pk_fma_f32 v[20:21], v[28:29], s[16:17], v[20:21] op_sel_hi:[1,0,1]
	v_pk_fma_f32 v[18:19], v[26:27], s[16:17], v[18:19] op_sel_hi:[1,0,1]
	v_add_f32_e32 v30, v30, v31
	v_add_f32_e32 v26, v18, v19
	v_add_f32_e32 v27, v20, v21
	v_add_f32_e32 v30, v30, v38
	v_mul_f32_e32 v31, v23, v23
	v_mul_f32_e32 v32, v25, v25
	v_add_f32_e32 v26, v26, v27
	v_fmac_f32_e32 v31, v22, v22
	v_fmac_f32_e32 v32, v24, v24
	v_add_f32_e32 v28, v26, v30
	v_mul_f32_e32 v26, v19, v19
	v_mul_f32_e32 v27, v21, v21
	v_add_f32_e32 v31, v31, v32
	v_fmac_f32_e32 v26, v18, v18
	v_fmac_f32_e32 v27, v20, v20
	v_add_f32_e32 v31, v39, v31
	v_add_f32_e32 v26, v26, v27
	v_add_f32_e32 v29, v26, v31
	v_pk_mul_f32 v[22:23], v[62:63], v[22:23]
	v_pk_mul_f32 v[26:27], v[60:61], v[20:21]
	v_pk_mul_f32 v[20:21], v[58:59], v[18:19]
	v_cvt_pk_bf16_f32 v18, v22, v23
	ds_bpermute_b32 v22, v214, v28
	ds_bpermute_b32 v23, v214, v29
	v_pk_mul_f32 v[24:25], v[64:65], v[24:25]
	s_nop 0
	v_cvt_pk_bf16_f32 v19, v24, v25
	v_cvt_pk_bf16_f32 v20, v20, v21
	v_cvt_pk_bf16_f32 v21, v26, v27
	global_store_dwordx4 v[34:35], v[18:21], off offset:256
	s_waitcnt lgkmcnt(1)
	s_nop 0
	v_add_f32_e32 v18, v28, v22
	s_waitcnt lgkmcnt(0)
	v_add_f32_e32 v19, v29, v23
	v_mov_b32_e32 v20, v18
	v_mov_b32_e32 v21, v19
	s_nop 0
	v_permlane32_swap_b32_e32 v18, v20
	v_permlane32_swap_b32_e32 v19, v21
	s_and_saveexec_b64 s[24:25], vcc
	s_cbranch_execz .LBB0_318
	v_add_f32_e32 v18, v18, v20
	v_add_f32_e32 v19, v19, v21
	ds_write_b64 v226, v[18:19] offset:1280
.LBB0_318:
	s_or_b64 exec, exec, s[24:25]
	s_waitcnt vmcnt(7)
	v_lshlrev_b32_e32 v24, 16, v86
	v_and_b32_e32 v25, 0xffff0000, v86
	v_lshlrev_b32_e32 v26, 16, v87
	v_and_b32_e32 v27, 0xffff0000, v87
	v_lshlrev_b32_e32 v20, 16, v88
	v_and_b32_e32 v21, 0xffff0000, v88
	v_lshlrev_b32_e32 v22, 16, v89
	v_and_b32_e32 v23, 0xffff0000, v89
	v_pk_fma_f32 v[16:17], v[26:27], s[16:17], v[16:17] op_sel_hi:[1,0,1]
	v_pk_fma_f32 v[14:15], v[24:25], s[16:17], v[14:15] op_sel_hi:[1,0,1]
	v_add_f32_e32 v25, v16, v17
	v_add_f32_e32 v24, v14, v15
	v_pk_fma_f32 v[12:13], v[22:23], s[16:17], v[12:13] op_sel_hi:[1,0,1]
	v_pk_fma_f32 v[10:11], v[20:21], s[16:17], v[10:11] op_sel_hi:[1,0,1]
	v_add_f32_e32 v24, v24, v25
	v_add_f32_e32 v20, v10, v11
	v_add_f32_e32 v21, v12, v13
	v_add_f32_e32 v24, 0, v24
	v_add_f32_e32 v20, v20, v21
	v_mul_f32_e32 v25, v15, v15
	v_mul_f32_e32 v26, v17, v17
	v_add_f32_e32 v22, v20, v24
	v_mul_f32_e32 v20, v11, v11
	v_mul_f32_e32 v21, v13, v13
	v_fmac_f32_e32 v25, v14, v14
	v_fmac_f32_e32 v26, v16, v16
	v_fmac_f32_e32 v20, v10, v10
	v_fmac_f32_e32 v21, v12, v12
	v_add_f32_e32 v25, v25, v26
	v_add_f32_e32 v20, v20, v21
	v_add_f32_e32 v23, v25, v20
	v_pk_mul_f32 v[16:17], v[72:73], v[16:17]
	v_pk_mul_f32 v[14:15], v[70:71], v[14:15]
	v_pk_mul_f32 v[20:21], v[68:69], v[12:13]
	v_pk_mul_f32 v[12:13], v[66:67], v[10:11]
	v_lshl_add_u64 v[18:19], v[192:193], 0, v[114:115]
	v_cvt_pk_bf16_f32 v10, v14, v15
	v_cvt_pk_bf16_f32 v11, v16, v17
	v_cvt_pk_bf16_f32 v12, v12, v13
	v_cvt_pk_bf16_f32 v13, v20, v21
	s_waitcnt vmcnt(6)
	v_lshlrev_b32_e32 v14, 16, v82
	v_and_b32_e32 v15, 0xffff0000, v82
	v_lshlrev_b32_e32 v16, 16, v83
	v_and_b32_e32 v17, 0xffff0000, v83
	global_store_dwordx4 v[18:19], v[10:13], off
	v_pk_fma_f32 v[8:9], v[16:17], s[16:17], v[8:9] op_sel_hi:[1,0,1]
	v_pk_fma_f32 v[6:7], v[14:15], s[16:17], v[6:7] op_sel_hi:[1,0,1]
	v_lshlrev_b32_e32 v10, 16, v84
	v_and_b32_e32 v11, 0xffff0000, v84
	v_lshlrev_b32_e32 v12, 16, v85
	v_and_b32_e32 v13, 0xffff0000, v85
	v_add_f32_e32 v14, v6, v7
	v_add_f32_e32 v15, v8, v9
	v_pk_fma_f32 v[4:5], v[12:13], s[16:17], v[4:5] op_sel_hi:[1,0,1]
	v_pk_fma_f32 v[2:3], v[10:11], s[16:17], v[2:3] op_sel_hi:[1,0,1]
	v_add_f32_e32 v14, v14, v15
	v_add_f32_e32 v10, v2, v3
	v_add_f32_e32 v11, v4, v5
	v_add_f32_e32 v14, v14, v22
	v_mul_f32_e32 v15, v7, v7
	v_mul_f32_e32 v16, v9, v9
	v_add_f32_e32 v10, v10, v11
	v_fmac_f32_e32 v15, v6, v6
	v_fmac_f32_e32 v16, v8, v8
	v_add_f32_e32 v12, v10, v14
	v_mul_f32_e32 v10, v3, v3
	v_mul_f32_e32 v11, v5, v5
	v_add_f32_e32 v15, v15, v16
	v_fmac_f32_e32 v10, v2, v2
	v_fmac_f32_e32 v11, v4, v4
	v_add_f32_e32 v15, v23, v15
	v_add_f32_e32 v10, v10, v11
	v_add_f32_e32 v13, v10, v15
	v_pk_mul_f32 v[6:7], v[62:63], v[6:7]
	v_pk_mul_f32 v[10:11], v[60:61], v[4:5]
	v_pk_mul_f32 v[4:5], v[58:59], v[2:3]
	v_cvt_pk_bf16_f32 v2, v6, v7
	ds_bpermute_b32 v6, v214, v12
	ds_bpermute_b32 v7, v214, v13
	v_pk_mul_f32 v[8:9], v[64:65], v[8:9]
	s_nop 0
	v_cvt_pk_bf16_f32 v3, v8, v9
	v_cvt_pk_bf16_f32 v4, v4, v5
	v_cvt_pk_bf16_f32 v5, v10, v11
	global_store_dwordx4 v[18:19], v[2:5], off offset:256
	s_waitcnt lgkmcnt(1)
	s_nop 0
	v_add_f32_e32 v2, v12, v6
	s_waitcnt lgkmcnt(0)
	v_add_f32_e32 v3, v13, v7
	v_mov_b32_e32 v4, v2
	v_mov_b32_e32 v5, v3
	s_nop 0
	v_permlane32_swap_b32_e32 v2, v4
	v_permlane32_swap_b32_e32 v3, v5
	s_and_saveexec_b64 s[24:25], vcc
	s_cbranch_execz .LBB0_320
	v_add_f32_e32 v2, v2, v4
	v_add_f32_e32 v3, v3, v5
	ds_write_b64 v226, v[2:3] offset:1408
.LBB0_320:
	s_or_b64 exec, exec, s[24:25]
	s_waitcnt lgkmcnt(0)
	s_barrier
	s_lshr_b32 s100, s53, 2
	v_lshl_add_u32 v8, v179, 4, v181
	v_lshl_add_u32 v8, v8, 2, s100
	v_add_u32_e32 v9, 0x20200, v8
	ds_read_b32 v10, v9
	ds_read_b32 v11, v9 offset:2048
	ds_read_b32 v12, v9 offset:4096
	ds_read_b32 v13, v9 offset:6144
	s_lshl_b32 s100, s76, 11
	v_add_u32_e32 v8, s100, v8
	s_waitcnt lgkmcnt(0)
	v_add_f32_e32 v10, v10, v11
	v_add_f32_e32 v12, v12, v13
	v_add_f32_e32 v10, v10, v12
	global_atomic_add_f32 v8, v10, s[64:65]
	s_and_b64 vcc, exec, s[6:7]
	s_mov_b64 s[6:7], -1
	s_cbranch_vccnz .LBB0_289
	s_and_b64 vcc, exec, s[4:5]
	s_cbranch_vccnz .LBB0_288
	s_barrier
	s_branch .LBB0_288

.LBB0_478:
	v_mov_b32_e32 v132, v164
	v_mov_b32_e32 v130, v165
	s_lshl_b32 s0, s2, 8
	s_add_i32 s0, s0, s54
	v_add_u32_e32 v156, s0, v130
	v_lshlrev_b32_e32 v154, 3, v132
	v_readlane_b32 s0, v255, 19
	s_cmp_gt_i32 s34, 9
	v_lshlrev_b32_e32 v130, 1, v132
	v_add_u32_e32 v152, s0, v154
	s_cselect_b64 s[24:25], -1, 0
	s_cmp_gt_u32 s34, 17
	v_ashrrev_i32_e32 v131, 31, v130
	v_readlane_b32 s0, v255, 13
	s_cselect_b64 s[36:37], -1, 0
	v_lshlrev_b64 v[160:161], 4, v[130:131]
	v_readlane_b32 s1, v255, 14
	s_cmp_lt_i32 s34, 22
	s_cselect_b64 s[40:41], -1, 0
	v_lshl_add_u64 v[158:159], s[0:1], 0, v[160:161]
	s_cmp_gt_i32 s34, 21
	v_readlane_b32 s0, v255, 15
	s_cselect_b64 s[46:47], -1, 0
	v_cmp_gt_i32_e32 vcc, 2, v132
	v_readlane_b32 s1, v255, 16
	s_lshl_b32 s50, s34, 8
	s_and_b64 s[84:85], s[0:1], vcc
	s_add_i32 s2, s50, 0xffffee00
	s_cmp_gt_i32 s34, 7
	s_cselect_b64 s[8:9], -1, 0
	s_cmp_lt_i32 s34, 8
	v_ashrrev_i32_e32 v155, 31, v154
	v_ashrrev_i32_e32 v153, 31, v152
	s_mov_b32 s51, s3
	s_cselect_b64 s[0:1], -1, 0
	v_ashrrev_i32_e32 v157, 31, v156
	s_cmp_gt_i32 s34, 9
	s_cbranch_scc0 .Lina_pf128
	s_cmp_gt_u32 s34, 17
	s_cbranch_scc0 .Lina_pf_done
	v_lshlrev_b64 v[248:249], 8, v[156:157]
	v_lshl_add_u64 v[248:249], v[158:159], 0, v[248:249]
	s_mov_b32 s100, 0x1000
	s_mov_b32 s101, 0
	s_mov_b32 s98, 0x5000
	s_mov_b32 s99, 0
	s_branch .Lina_pf_issue
.Lina_pf128:
	v_readlane_b32 s100, v255, 11
	v_readlane_b32 s101, v255, 12
	v_lshlrev_b64 v[248:249], 9, v[156:157]
	s_nop 1
	v_lshl_add_u64 v[250:251], s[100:101], 0, v[160:161]
	v_lshl_add_u64 v[248:249], v[250:251], 0, v[248:249]
	s_mov_b32 s100, 0x2000
	s_mov_b32 s101, 0
	s_mov_b32 s98, 0xa000
	s_mov_b32 s99, 0
.Lina_pf_issue:
	global_load_dwordx4 v[182:185], v[248:249], off
	global_load_dwordx4 v[186:189], v[248:249], off offset:16
	v_lshl_add_u64 v[248:249], v[248:249], 0, s[100:101]
	global_load_dwordx4 v[190:193], v[248:249], off
	global_load_dwordx4 v[194:197], v[248:249], off offset:16
	v_lshl_add_u64 v[248:249], v[248:249], 0, s[100:101]
	global_load_dwordx4 v[198:201], v[248:249], off
	global_load_dwordx4 v[202:205], v[248:249], off offset:16
	v_lshl_add_u64 v[248:249], v[248:249], 0, s[100:101]
	global_load_dwordx4 v[206:209], v[248:249], off
	global_load_dwordx4 v[210:213], v[248:249], off offset:16
	v_lshl_add_u64 v[248:249], v[248:249], 0, s[98:99]
	global_load_dwordx4 v[214:217], v[248:249], off
	global_load_dwordx4 v[218:221], v[248:249], off offset:16
	v_lshl_add_u64 v[248:249], v[248:249], 0, s[100:101]
	global_load_dwordx4 v[222:225], v[248:249], off
	global_load_dwordx4 v[226:229], v[248:249], off offset:16
	v_lshl_add_u64 v[248:249], v[248:249], 0, s[100:101]
	global_load_dwordx4 v[232:235], v[248:249], off
	global_load_dwordx4 v[236:239], v[248:249], off offset:16
	v_lshl_add_u64 v[248:249], v[248:249], 0, s[100:101]
	global_load_dwordx4 v[240:243], v[248:249], off
	global_load_dwordx4 v[248:251], v[248:249], off offset:16
	s_waitcnt vmcnt(0)
.Lina_pf_done:
	s_and_b64 vcc, exec, s[24:25]
	s_cbranch_vccz .LBB0_492
	s_and_b64 vcc, exec, s[36:37]
	s_cbranch_vccz .LBB0_493
	v_lshlrev_b64 v[130:131], 8, v[156:157]
	v_lshl_add_u64 v[134:135], v[158:159], 0, v[130:131]
	s_nop 0
	s_mov_b64 s[10:11], -1
	s_and_b64 vcc, exec, s[46:47]
	v_mov_b64_e32 v[130:131], v[186:187]
	v_mov_b64_e32 v[132:133], v[188:189]
	v_mov_b64_e32 v[134:135], v[182:183]
	v_mov_b64_e32 v[136:137], v[184:185]
	v_pk_mul_f32 v[138:139], v[126:127], v[134:135]
	v_pk_mul_f32 v[140:141], v[128:129], v[136:137]
	v_sub_f32_e32 v162, v138, v139
	v_pk_mul_f32 v[138:139], v[126:127], v[134:135] op_sel:[1,0] op_sel_hi:[0,1]
	v_add_f32_e32 v138, v138, v139
	v_sub_f32_e32 v139, v140, v141
	v_pk_mul_f32 v[140:141], v[128:129], v[136:137] op_sel:[1,0] op_sel_hi:[0,1]
	v_add_f32_e32 v140, v140, v141
	v_cvt_pk_bf16_f32 v138, v162, v138
	v_cvt_pk_bf16_f32 v139, v139, v140
	v_pk_mul_f32 v[140:141], v[122:123], v[130:131]
	v_pk_mul_f32 v[162:163], v[124:125], v[132:133]
	v_sub_f32_e32 v168, v140, v141
	v_pk_mul_f32 v[140:141], v[122:123], v[130:131] op_sel:[1,0] op_sel_hi:[0,1]
	v_add_f32_e32 v140, v140, v141
	v_sub_f32_e32 v141, v162, v163
	v_pk_mul_f32 v[162:163], v[124:125], v[132:133] op_sel:[1,0] op_sel_hi:[0,1]
	v_cvt_pk_bf16_f32 v140, v168, v140
	v_add_f32_e32 v162, v162, v163
	v_cvt_pk_bf16_f32 v141, v141, v162
	s_cbranch_vccz .LBB0_488
	v_readlane_b32 s34, v255, 17
	v_readlane_b32 s35, v255, 18
	s_and_b64 vcc, exec, s[34:35]
	s_cbranch_vccz .LBB0_485
	s_and_saveexec_b64 s[10:11], s[84:85]
	s_cbranch_execz .LBB0_484
	v_readlane_b32 s34, v255, 1
	v_lshlrev_b64 v[162:163], 4, v[156:157]
	v_readlane_b32 s35, v255, 2
	s_nop 1
	v_lshl_add_u64 v[162:163], v[162:163], 2, s[34:35]
	s_mov_b32 s34, 0x3d000000
	v_lshl_add_u64 v[162:163], v[154:155], 2, v[162:163]
	v_pk_mul_f32 v[174:175], v[128:129], s[34:35] op_sel_hi:[1,0]
	v_pk_mul_f32 v[172:173], v[126:127], s[34:35] op_sel_hi:[1,0]
	v_pk_mul_f32 v[170:171], v[124:125], s[34:35] op_sel_hi:[1,0]
	v_pk_mul_f32 v[168:169], v[122:123], s[34:35] op_sel_hi:[1,0]
	global_store_dwordx4 v[162:163], v[172:175], off
	global_store_dwordx4 v[162:163], v[168:171], off offset:16

.LBB0_497:
	v_readlane_b32 s68, v255, 11
	v_readlane_b32 s69, v255, 12
	v_cndmask_b32_e64 v138, 1.0, v246, s[0:1]
	s_ashr_i32 s1, s50, 31
	v_lshl_add_u64 v[140:141], s[68:69], 0, v[160:161]
	s_mov_b32 s0, s50
	v_mov_b32_e32 v139, v138
	s_and_b64 vcc, exec, s[34:35]
	s_cbranch_vccz .LBB0_503
	v_lshlrev_b64 v[130:131], 9, v[156:157]
	v_lshl_add_u64 v[134:135], v[140:141], 0, v[130:131]
	s_nop 0
	s_mov_b64 s[10:11], -1
	s_and_b64 vcc, exec, s[8:9]
	s_cbranch_vccz .LBB0_500
	v_lshlrev_b64 v[160:161], 10, v[156:157]
	v_lshl_add_u64 v[160:161], s[22:23], 0, v[160:161]
	v_lshl_add_u64 v[160:161], s[50:51], 1, v[160:161]
	s_mov_b64 s[10:11], 0x2e5ff000
	v_lshl_add_u64 v[160:161], v[160:161], 0, s[10:11]
	s_mov_b64 s[10:11], 0

.LBB0_502:
	v_mov_b32_e32 v162, v138
	v_mov_b32_e32 v163, v138
	v_pk_mul_f32 v[126:127], v[138:139], v[126:127]
	v_pk_mul_f32 v[128:129], v[162:163], v[128:129]
	v_pk_mul_f32 v[168:169], v[162:163], v[124:125]
	v_pk_mul_f32 v[124:125], v[138:139], v[122:123]
	v_mov_b64_e32 v[130:131], v[186:187]
	v_mov_b64_e32 v[132:133], v[188:189]
	v_mov_b64_e32 v[134:135], v[182:183]
	v_mov_b64_e32 v[136:137], v[184:185]
	v_pk_mul_f32 v[122:123], v[126:127], v[134:135]
	v_pk_mul_f32 v[170:171], v[128:129], v[136:137]
	v_sub_f32_e32 v157, v122, v123
	v_pk_mul_f32 v[122:123], v[126:127], v[134:135] op_sel:[1,0] op_sel_hi:[0,1]
	v_pk_mul_f32 v[126:127], v[128:129], v[136:137] op_sel:[1,0] op_sel_hi:[0,1]
	v_add_f32_e32 v122, v122, v123
	v_sub_f32_e32 v123, v170, v171
	v_add_f32_e32 v126, v126, v127
	v_cvt_pk_bf16_f32 v122, v157, v122
	v_cvt_pk_bf16_f32 v123, v123, v126
	v_pk_mul_f32 v[126:127], v[168:169], v[132:133]
	v_pk_mul_f32 v[128:129], v[124:125], v[130:131]
	v_pk_mul_f32 v[124:125], v[124:125], v[130:131] op_sel:[1,0] op_sel_hi:[0,1]
	v_add_f32_e32 v124, v124, v125
	v_sub_f32_e32 v125, v126, v127
	v_pk_mul_f32 v[126:127], v[168:169], v[132:133] op_sel:[1,0] op_sel_hi:[0,1]
	v_lshl_add_u64 v[160:161], v[152:153], 1, v[160:161]
	v_sub_f32_e32 v128, v128, v129
	v_cvt_pk_bf16_f32 v124, v128, v124
	v_add_f32_e32 v126, v126, v127
	v_cvt_pk_bf16_f32 v125, v125, v126
	v_pk_mul_f32 v[118:119], v[138:139], v[118:119]
	global_store_dwordx4 v[160:161], v[122:125], off
	v_pk_mul_f32 v[120:121], v[162:163], v[120:121]
	v_pk_mul_f32 v[114:115], v[138:139], v[114:115]
	v_pk_mul_f32 v[124:125], v[118:119], v[134:135]
	v_pk_mul_f32 v[118:119], v[118:119], v[134:135] op_sel:[1,0] op_sel_hi:[0,1]
	v_add_f32_e32 v118, v118, v119
	v_pk_mul_f32 v[122:123], v[120:121], v[136:137]
	v_sub_f32_e32 v124, v124, v125
	v_cvt_pk_bf16_f32 v134, v124, v118
	v_pk_mul_f32 v[118:119], v[120:121], v[136:137] op_sel:[1,0] op_sel_hi:[0,1]
	v_pk_mul_f32 v[120:121], v[114:115], v[130:131]
	v_pk_mul_f32 v[114:115], v[114:115], v[130:131] op_sel:[1,0] op_sel_hi:[0,1]
	v_pk_mul_f32 v[116:117], v[162:163], v[116:117]
	v_add_f32_e32 v118, v118, v119
	v_add_f32_e32 v114, v114, v115
	v_sub_f32_e32 v122, v122, v123
	v_cvt_pk_bf16_f32 v135, v122, v118
	v_pk_mul_f32 v[118:119], v[116:117], v[132:133]
	v_sub_f32_e32 v120, v120, v121
	v_cvt_pk_bf16_f32 v136, v120, v114
	v_pk_mul_f32 v[114:115], v[116:117], v[132:133] op_sel:[1,0] op_sel_hi:[0,1]
	s_mov_b64 s[10:11], 0x100
	v_sub_f32_e32 v118, v118, v119
	v_add_f32_e32 v114, v114, v115
	v_cvt_pk_bf16_f32 v137, v118, v114
	v_lshl_add_u64 v[130:131], v[160:161], 0, s[10:11]
	s_mov_b64 s[10:11], -1

.LBB0_505:
	v_add_u32_e32 v126, 16, v156
	v_cndmask_b32_e64 v114, 0, 1, s[24:25]
	v_cmp_ne_u32_e64 s[10:11], 1, v114
	s_andn2_b64 vcc, exec, s[24:25]
	v_ashrrev_i32_e32 v127, 31, v126
	s_cbranch_vccnz .LBB0_519
	s_and_b64 vcc, exec, s[36:37]
	s_cbranch_vccz .LBB0_520
	v_lshlrev_b64 v[114:115], 8, v[126:127]
	v_lshl_add_u64 v[114:115], v[158:159], 0, v[114:115]
	s_nop 0
	s_andn2_b64 vcc, exec, s[46:47]
	s_mov_b64 s[24:25], -1
	v_mov_b64_e32 v[118:119], v[190:191]
	v_mov_b64_e32 v[120:121], v[192:193]
	v_mov_b64_e32 v[114:115], v[194:195]
	v_mov_b64_e32 v[116:117], v[196:197]
	v_pk_mul_f32 v[122:123], v[112:113], v[120:121]
	v_pk_mul_f32 v[124:125], v[110:111], v[118:119]
	v_pk_mul_f32 v[128:129], v[110:111], v[118:119] op_sel:[1,0] op_sel_hi:[0,1]
	v_pk_mul_f32 v[130:131], v[112:113], v[120:121] op_sel:[1,0] op_sel_hi:[0,1]
	v_pk_mul_f32 v[132:133], v[108:109], v[116:117]
	v_pk_mul_f32 v[134:135], v[106:107], v[114:115]
	v_pk_mul_f32 v[136:137], v[106:107], v[114:115] op_sel:[1,0] op_sel_hi:[0,1]
	v_pk_mul_f32 v[160:161], v[108:109], v[116:117] op_sel:[1,0] op_sel_hi:[0,1]
	v_sub_f32_e32 v124, v124, v125
	v_add_f32_e32 v125, v128, v129
	v_sub_f32_e32 v123, v122, v123
	v_add_f32_e32 v128, v130, v131
	v_sub_f32_e32 v129, v134, v135
	v_add_f32_e32 v130, v136, v137
	v_sub_f32_e32 v131, v132, v133
	v_add_f32_e32 v132, v160, v161
	v_cvt_pk_bf16_f32 v122, v124, v125
	v_cvt_pk_bf16_f32 v123, v123, v128
	v_cvt_pk_bf16_f32 v124, v129, v130
	v_cvt_pk_bf16_f32 v125, v131, v132
	s_cbranch_vccnz .LBB0_515
	v_readlane_b32 s24, v255, 17
	v_readlane_b32 s25, v255, 18
	s_andn2_b64 vcc, exec, s[24:25]
	s_mov_b64 s[24:25], -1
	s_cbranch_vccnz .LBB0_512
	s_and_saveexec_b64 s[24:25], s[84:85]
	s_cbranch_execz .LBB0_511
	v_readlane_b32 s34, v255, 1
	v_lshlrev_b64 v[128:129], 4, v[126:127]
	v_readlane_b32 s35, v255, 2
	s_nop 1
	v_lshl_add_u64 v[128:129], v[128:129], 2, s[34:35]
	s_mov_b32 s34, 0x3d000000
	v_lshl_add_u64 v[136:137], v[154:155], 2, v[128:129]
	v_pk_mul_f32 v[134:135], v[112:113], s[34:35] op_sel_hi:[1,0]
	v_pk_mul_f32 v[132:133], v[110:111], s[34:35] op_sel_hi:[1,0]
	v_pk_mul_f32 v[130:131], v[108:109], s[34:35] op_sel_hi:[1,0]
	v_pk_mul_f32 v[128:129], v[106:107], s[34:35] op_sel_hi:[1,0]
	global_store_dwordx4 v[136:137], v[132:135], off
	global_store_dwordx4 v[136:137], v[128:131], off offset:16

.LBB0_524:
	v_lshlrev_b64 v[114:115], 9, v[126:127]
	v_lshl_add_u64 v[118:119], v[140:141], 0, v[114:115]
	s_nop 0
	s_and_b64 vcc, exec, s[8:9]
	s_mov_b64 s[24:25], -1
	s_cbranch_vccnz .LBB0_526
	v_lshlrev_b64 v[122:123], 10, v[126:127]
	v_lshl_add_u64 v[122:123], s[22:23], 0, v[122:123]
	v_lshl_add_u64 v[122:123], s[50:51], 1, v[122:123]
	s_mov_b64 s[24:25], 0x2e5ff000
	v_lshl_add_u64 v[122:123], v[122:123], 0, s[24:25]
	s_mov_b64 s[24:25], 0

.LBB0_528:
	v_mov_b32_e32 v124, v138
	v_mov_b32_e32 v125, v138
	v_pk_mul_f32 v[110:111], v[138:139], v[110:111]
	v_pk_mul_f32 v[112:113], v[124:125], v[112:113]
	v_pk_mul_f32 v[126:127], v[124:125], v[108:109]
	v_pk_mul_f32 v[108:109], v[138:139], v[106:107]
	v_mov_b64_e32 v[114:115], v[194:195]
	v_mov_b64_e32 v[116:117], v[196:197]
	v_mov_b64_e32 v[118:119], v[190:191]
	v_mov_b64_e32 v[120:121], v[192:193]
	v_pk_mul_f32 v[106:107], v[110:111], v[118:119]
	v_pk_mul_f32 v[128:129], v[112:113], v[120:121]
	v_sub_f32_e32 v130, v106, v107
	v_pk_mul_f32 v[106:107], v[110:111], v[118:119] op_sel:[1,0] op_sel_hi:[0,1]
	v_pk_mul_f32 v[110:111], v[112:113], v[120:121] op_sel:[1,0] op_sel_hi:[0,1]
	v_add_f32_e32 v106, v106, v107
	v_sub_f32_e32 v107, v128, v129
	v_add_f32_e32 v110, v110, v111
	v_cvt_pk_bf16_f32 v106, v130, v106
	v_cvt_pk_bf16_f32 v107, v107, v110
	v_pk_mul_f32 v[110:111], v[126:127], v[116:117]
	v_pk_mul_f32 v[112:113], v[108:109], v[114:115]
	v_pk_mul_f32 v[108:109], v[108:109], v[114:115] op_sel:[1,0] op_sel_hi:[0,1]
	v_add_f32_e32 v108, v108, v109
	v_sub_f32_e32 v109, v110, v111
	v_pk_mul_f32 v[110:111], v[126:127], v[116:117] op_sel:[1,0] op_sel_hi:[0,1]
	v_lshl_add_u64 v[122:123], v[152:153], 1, v[122:123]
	v_sub_f32_e32 v112, v112, v113
	v_cvt_pk_bf16_f32 v108, v112, v108
	v_add_f32_e32 v110, v110, v111
	v_cvt_pk_bf16_f32 v109, v109, v110
	v_pk_mul_f32 v[102:103], v[138:139], v[102:103]
	global_store_dwordx4 v[122:123], v[106:109], off
	v_pk_mul_f32 v[104:105], v[124:125], v[104:105]
	v_pk_mul_f32 v[98:99], v[138:139], v[98:99]
	v_pk_mul_f32 v[108:109], v[102:103], v[118:119]
	v_pk_mul_f32 v[102:103], v[102:103], v[118:119] op_sel:[1,0] op_sel_hi:[0,1]
	v_add_f32_e32 v102, v102, v103
	v_pk_mul_f32 v[106:107], v[104:105], v[120:121]
	v_sub_f32_e32 v108, v108, v109
	v_cvt_pk_bf16_f32 v118, v108, v102
	v_pk_mul_f32 v[102:103], v[104:105], v[120:121] op_sel:[1,0] op_sel_hi:[0,1]
	v_pk_mul_f32 v[104:105], v[98:99], v[114:115]
	v_pk_mul_f32 v[98:99], v[98:99], v[114:115] op_sel:[1,0] op_sel_hi:[0,1]
	v_pk_mul_f32 v[100:101], v[124:125], v[100:101]
	v_add_f32_e32 v102, v102, v103
	v_add_f32_e32 v98, v98, v99
	s_mov_b64 s[24:25], 0x100
	v_sub_f32_e32 v106, v106, v107
	v_cvt_pk_bf16_f32 v119, v106, v102
	v_pk_mul_f32 v[102:103], v[100:101], v[116:117]
	v_sub_f32_e32 v104, v104, v105
	v_cvt_pk_bf16_f32 v120, v104, v98
	v_pk_mul_f32 v[98:99], v[100:101], v[116:117] op_sel:[1,0] op_sel_hi:[0,1]
	v_lshl_add_u64 v[114:115], v[122:123], 0, s[24:25]
	s_mov_b64 s[24:25], -1
	v_sub_f32_e32 v102, v102, v103
	v_add_f32_e32 v98, v98, v99
	v_cvt_pk_bf16_f32 v121, v102, v98

.LBB0_531:
	s_and_b64 vcc, exec, s[36:37]
	s_cbranch_vccz .LBB0_546
	v_lshlrev_b64 v[98:99], 8, v[110:111]
	v_lshl_add_u64 v[98:99], v[158:159], 0, v[98:99]
	s_nop 0
	s_andn2_b64 vcc, exec, s[46:47]
	s_mov_b64 s[24:25], -1
	v_mov_b64_e32 v[102:103], v[198:199]
	v_mov_b64_e32 v[104:105], v[200:201]
	v_mov_b64_e32 v[98:99], v[202:203]
	v_mov_b64_e32 v[100:101], v[204:205]
	v_pk_mul_f32 v[106:107], v[96:97], v[104:105]
	v_pk_mul_f32 v[108:109], v[94:95], v[102:103]
	v_pk_mul_f32 v[112:113], v[94:95], v[102:103] op_sel:[1,0] op_sel_hi:[0,1]
	v_pk_mul_f32 v[114:115], v[96:97], v[104:105] op_sel:[1,0] op_sel_hi:[0,1]
	v_pk_mul_f32 v[116:117], v[92:93], v[100:101]
	v_pk_mul_f32 v[118:119], v[90:91], v[98:99]
	v_pk_mul_f32 v[120:121], v[90:91], v[98:99] op_sel:[1,0] op_sel_hi:[0,1]
	v_pk_mul_f32 v[122:123], v[92:93], v[100:101] op_sel:[1,0] op_sel_hi:[0,1]
	v_sub_f32_e32 v108, v108, v109
	v_add_f32_e32 v109, v112, v113
	v_sub_f32_e32 v107, v106, v107
	v_add_f32_e32 v112, v114, v115
	v_sub_f32_e32 v113, v118, v119
	v_add_f32_e32 v114, v120, v121
	v_sub_f32_e32 v115, v116, v117
	v_add_f32_e32 v116, v122, v123
	v_cvt_pk_bf16_f32 v106, v108, v109
	v_cvt_pk_bf16_f32 v107, v107, v112
	v_cvt_pk_bf16_f32 v108, v113, v114
	v_cvt_pk_bf16_f32 v109, v115, v116
	s_cbranch_vccnz .LBB0_540
	v_readlane_b32 s24, v255, 17
	v_readlane_b32 s25, v255, 18
	s_andn2_b64 vcc, exec, s[24:25]
	s_mov_b64 s[24:25], -1
	s_cbranch_vccnz .LBB0_537
	s_and_saveexec_b64 s[24:25], s[84:85]
	s_cbranch_execz .LBB0_536
	v_readlane_b32 s34, v255, 1
	v_lshlrev_b64 v[112:113], 4, v[110:111]
	v_readlane_b32 s35, v255, 2
	s_nop 1
	v_lshl_add_u64 v[112:113], v[112:113], 2, s[34:35]
	s_mov_b32 s34, 0x3d000000
	v_lshl_add_u64 v[120:121], v[154:155], 2, v[112:113]
	v_pk_mul_f32 v[118:119], v[96:97], s[34:35] op_sel_hi:[1,0]
	v_pk_mul_f32 v[116:117], v[94:95], s[34:35] op_sel_hi:[1,0]
	v_pk_mul_f32 v[114:115], v[92:93], s[34:35] op_sel_hi:[1,0]
	v_pk_mul_f32 v[112:113], v[90:91], s[34:35] op_sel_hi:[1,0]
	global_store_dwordx4 v[120:121], v[116:119], off
	global_store_dwordx4 v[120:121], v[112:115], off offset:16

.LBB0_550:
	v_lshlrev_b64 v[98:99], 9, v[110:111]
	v_lshl_add_u64 v[102:103], v[140:141], 0, v[98:99]
	s_nop 0
	s_and_b64 vcc, exec, s[8:9]
	s_mov_b64 s[24:25], -1
	s_cbranch_vccnz .LBB0_552
	v_lshlrev_b64 v[106:107], 10, v[110:111]
	v_lshl_add_u64 v[106:107], s[22:23], 0, v[106:107]
	v_lshl_add_u64 v[106:107], s[50:51], 1, v[106:107]
	s_mov_b64 s[24:25], 0x2e5ff000
	v_lshl_add_u64 v[106:107], v[106:107], 0, s[24:25]
	s_mov_b64 s[24:25], 0

.LBB0_554:
	v_mov_b32_e32 v108, v138
	v_mov_b32_e32 v109, v138
	v_pk_mul_f32 v[94:95], v[138:139], v[94:95]
	v_pk_mul_f32 v[96:97], v[108:109], v[96:97]
	v_pk_mul_f32 v[110:111], v[108:109], v[92:93]
	v_pk_mul_f32 v[92:93], v[138:139], v[90:91]
	v_mov_b64_e32 v[98:99], v[202:203]
	v_mov_b64_e32 v[100:101], v[204:205]
	v_mov_b64_e32 v[102:103], v[198:199]
	v_mov_b64_e32 v[104:105], v[200:201]
	v_pk_mul_f32 v[90:91], v[94:95], v[102:103]
	v_pk_mul_f32 v[112:113], v[96:97], v[104:105]
	v_sub_f32_e32 v114, v90, v91
	v_pk_mul_f32 v[90:91], v[94:95], v[102:103] op_sel:[1,0] op_sel_hi:[0,1]
	v_pk_mul_f32 v[94:95], v[96:97], v[104:105] op_sel:[1,0] op_sel_hi:[0,1]
	v_add_f32_e32 v90, v90, v91
	v_sub_f32_e32 v91, v112, v113
	v_add_f32_e32 v94, v94, v95
	v_cvt_pk_bf16_f32 v90, v114, v90
	v_cvt_pk_bf16_f32 v91, v91, v94
	v_pk_mul_f32 v[94:95], v[110:111], v[100:101]
	v_pk_mul_f32 v[96:97], v[92:93], v[98:99]
	v_pk_mul_f32 v[92:93], v[92:93], v[98:99] op_sel:[1,0] op_sel_hi:[0,1]
	v_add_f32_e32 v92, v92, v93
	v_sub_f32_e32 v93, v94, v95
	v_pk_mul_f32 v[94:95], v[110:111], v[100:101] op_sel:[1,0] op_sel_hi:[0,1]
	v_lshl_add_u64 v[106:107], v[152:153], 1, v[106:107]
	v_sub_f32_e32 v96, v96, v97
	v_cvt_pk_bf16_f32 v92, v96, v92
	v_add_f32_e32 v94, v94, v95
	v_cvt_pk_bf16_f32 v93, v93, v94
	v_pk_mul_f32 v[86:87], v[138:139], v[86:87]
	global_store_dwordx4 v[106:107], v[90:93], off
	v_pk_mul_f32 v[88:89], v[108:109], v[88:89]
	v_pk_mul_f32 v[82:83], v[138:139], v[82:83]
	v_pk_mul_f32 v[92:93], v[86:87], v[102:103]
	v_pk_mul_f32 v[86:87], v[86:87], v[102:103] op_sel:[1,0] op_sel_hi:[0,1]
	v_add_f32_e32 v86, v86, v87
	v_pk_mul_f32 v[90:91], v[88:89], v[104:105]
	v_sub_f32_e32 v92, v92, v93
	v_cvt_pk_bf16_f32 v102, v92, v86
	v_pk_mul_f32 v[86:87], v[88:89], v[104:105] op_sel:[1,0] op_sel_hi:[0,1]
	v_pk_mul_f32 v[88:89], v[82:83], v[98:99]
	v_pk_mul_f32 v[82:83], v[82:83], v[98:99] op_sel:[1,0] op_sel_hi:[0,1]
	v_pk_mul_f32 v[84:85], v[108:109], v[84:85]
	v_add_f32_e32 v86, v86, v87
	v_add_f32_e32 v82, v82, v83
	s_mov_b64 s[24:25], 0x100
	v_sub_f32_e32 v90, v90, v91
	v_cvt_pk_bf16_f32 v103, v90, v86
	v_pk_mul_f32 v[86:87], v[84:85], v[100:101]
	v_sub_f32_e32 v88, v88, v89
	v_cvt_pk_bf16_f32 v104, v88, v82
	v_pk_mul_f32 v[82:83], v[84:85], v[100:101] op_sel:[1,0] op_sel_hi:[0,1]
	v_lshl_add_u64 v[98:99], v[106:107], 0, s[24:25]
	s_mov_b64 s[24:25], -1
	v_sub_f32_e32 v86, v86, v87
	v_add_f32_e32 v82, v82, v83
	v_cvt_pk_bf16_f32 v105, v86, v82

.LBB0_557:
	s_and_b64 vcc, exec, s[36:37]
	s_cbranch_vccz .LBB0_572
	v_lshlrev_b64 v[82:83], 8, v[94:95]
	v_lshl_add_u64 v[82:83], v[158:159], 0, v[82:83]
	s_nop 0
	s_andn2_b64 vcc, exec, s[46:47]
	s_mov_b64 s[24:25], -1
	v_mov_b64_e32 v[86:87], v[206:207]
	v_mov_b64_e32 v[88:89], v[208:209]
	v_mov_b64_e32 v[82:83], v[210:211]
	v_mov_b64_e32 v[84:85], v[212:213]
	v_pk_mul_f32 v[90:91], v[80:81], v[88:89]
	v_pk_mul_f32 v[92:93], v[78:79], v[86:87]
	v_pk_mul_f32 v[96:97], v[78:79], v[86:87] op_sel:[1,0] op_sel_hi:[0,1]
	v_pk_mul_f32 v[98:99], v[80:81], v[88:89] op_sel:[1,0] op_sel_hi:[0,1]
	v_pk_mul_f32 v[100:101], v[76:77], v[84:85]
	v_pk_mul_f32 v[102:103], v[74:75], v[82:83]
	v_pk_mul_f32 v[104:105], v[74:75], v[82:83] op_sel:[1,0] op_sel_hi:[0,1]
	v_pk_mul_f32 v[106:107], v[76:77], v[84:85] op_sel:[1,0] op_sel_hi:[0,1]
	v_sub_f32_e32 v92, v92, v93
	v_add_f32_e32 v93, v96, v97
	v_sub_f32_e32 v91, v90, v91
	v_add_f32_e32 v96, v98, v99
	v_sub_f32_e32 v97, v102, v103
	v_add_f32_e32 v98, v104, v105
	v_sub_f32_e32 v99, v100, v101
	v_add_f32_e32 v100, v106, v107
	v_cvt_pk_bf16_f32 v90, v92, v93
	v_cvt_pk_bf16_f32 v91, v91, v96
	v_cvt_pk_bf16_f32 v92, v97, v98
	v_cvt_pk_bf16_f32 v93, v99, v100
	s_cbranch_vccnz .LBB0_566
	v_readlane_b32 s24, v255, 17
	v_readlane_b32 s25, v255, 18
	s_andn2_b64 vcc, exec, s[24:25]
	s_mov_b64 s[24:25], -1
	s_cbranch_vccnz .LBB0_563
	s_and_saveexec_b64 s[24:25], s[84:85]
	s_cbranch_execz .LBB0_562
	v_readlane_b32 s34, v255, 1
	v_lshlrev_b64 v[96:97], 4, v[94:95]
	v_readlane_b32 s35, v255, 2
	s_nop 1
	v_lshl_add_u64 v[96:97], v[96:97], 2, s[34:35]
	s_mov_b32 s34, 0x3d000000
	v_lshl_add_u64 v[104:105], v[154:155], 2, v[96:97]
	v_pk_mul_f32 v[102:103], v[80:81], s[34:35] op_sel_hi:[1,0]
	v_pk_mul_f32 v[100:101], v[78:79], s[34:35] op_sel_hi:[1,0]
	v_pk_mul_f32 v[98:99], v[76:77], s[34:35] op_sel_hi:[1,0]
	v_pk_mul_f32 v[96:97], v[74:75], s[34:35] op_sel_hi:[1,0]
	global_store_dwordx4 v[104:105], v[100:103], off
	global_store_dwordx4 v[104:105], v[96:99], off offset:16

.LBB0_576:
	v_lshlrev_b64 v[82:83], 9, v[94:95]
	v_lshl_add_u64 v[86:87], v[140:141], 0, v[82:83]
	s_nop 0
	s_and_b64 vcc, exec, s[8:9]
	s_mov_b64 s[24:25], -1
	s_cbranch_vccnz .LBB0_578
	v_lshlrev_b64 v[90:91], 10, v[94:95]
	v_lshl_add_u64 v[90:91], s[22:23], 0, v[90:91]
	v_lshl_add_u64 v[90:91], s[50:51], 1, v[90:91]
	s_mov_b64 s[24:25], 0x2e5ff000
	v_lshl_add_u64 v[90:91], v[90:91], 0, s[24:25]
	s_mov_b64 s[24:25], 0

.LBB0_580:
	v_mov_b32_e32 v92, v138
	v_mov_b32_e32 v93, v138
	v_pk_mul_f32 v[78:79], v[138:139], v[78:79]
	v_pk_mul_f32 v[80:81], v[92:93], v[80:81]
	v_pk_mul_f32 v[94:95], v[92:93], v[76:77]
	v_pk_mul_f32 v[76:77], v[138:139], v[74:75]
	v_mov_b64_e32 v[82:83], v[210:211]
	v_mov_b64_e32 v[84:85], v[212:213]
	v_mov_b64_e32 v[86:87], v[206:207]
	v_mov_b64_e32 v[88:89], v[208:209]
	v_pk_mul_f32 v[74:75], v[78:79], v[86:87]
	v_pk_mul_f32 v[96:97], v[80:81], v[88:89]
	v_sub_f32_e32 v98, v74, v75
	v_pk_mul_f32 v[74:75], v[78:79], v[86:87] op_sel:[1,0] op_sel_hi:[0,1]
	v_pk_mul_f32 v[78:79], v[80:81], v[88:89] op_sel:[1,0] op_sel_hi:[0,1]
	v_add_f32_e32 v74, v74, v75
	v_sub_f32_e32 v75, v96, v97
	v_add_f32_e32 v78, v78, v79
	v_cvt_pk_bf16_f32 v74, v98, v74
	v_cvt_pk_bf16_f32 v75, v75, v78
	v_pk_mul_f32 v[78:79], v[94:95], v[84:85]
	v_pk_mul_f32 v[80:81], v[76:77], v[82:83]
	v_pk_mul_f32 v[76:77], v[76:77], v[82:83] op_sel:[1,0] op_sel_hi:[0,1]
	v_add_f32_e32 v76, v76, v77
	v_sub_f32_e32 v77, v78, v79
	v_pk_mul_f32 v[78:79], v[94:95], v[84:85] op_sel:[1,0] op_sel_hi:[0,1]
	v_lshl_add_u64 v[90:91], v[152:153], 1, v[90:91]
	v_sub_f32_e32 v80, v80, v81
	v_cvt_pk_bf16_f32 v76, v80, v76
	v_add_f32_e32 v78, v78, v79
	v_cvt_pk_bf16_f32 v77, v77, v78
	v_pk_mul_f32 v[70:71], v[138:139], v[70:71]
	global_store_dwordx4 v[90:91], v[74:77], off
	v_pk_mul_f32 v[72:73], v[92:93], v[72:73]
	v_pk_mul_f32 v[66:67], v[138:139], v[66:67]
	v_pk_mul_f32 v[76:77], v[70:71], v[86:87]
	v_pk_mul_f32 v[70:71], v[70:71], v[86:87] op_sel:[1,0] op_sel_hi:[0,1]
	v_add_f32_e32 v70, v70, v71
	v_pk_mul_f32 v[74:75], v[72:73], v[88:89]
	v_sub_f32_e32 v76, v76, v77
	v_cvt_pk_bf16_f32 v86, v76, v70
	v_pk_mul_f32 v[70:71], v[72:73], v[88:89] op_sel:[1,0] op_sel_hi:[0,1]
	v_pk_mul_f32 v[72:73], v[66:67], v[82:83]
	v_pk_mul_f32 v[66:67], v[66:67], v[82:83] op_sel:[1,0] op_sel_hi:[0,1]
	v_pk_mul_f32 v[68:69], v[92:93], v[68:69]
	v_add_f32_e32 v70, v70, v71
	v_add_f32_e32 v66, v66, v67
	s_mov_b64 s[24:25], 0x100
	v_sub_f32_e32 v74, v74, v75
	v_cvt_pk_bf16_f32 v87, v74, v70
	v_pk_mul_f32 v[70:71], v[68:69], v[84:85]
	v_sub_f32_e32 v72, v72, v73
	v_cvt_pk_bf16_f32 v88, v72, v66
	v_pk_mul_f32 v[66:67], v[68:69], v[84:85] op_sel:[1,0] op_sel_hi:[0,1]
	v_lshl_add_u64 v[82:83], v[90:91], 0, s[24:25]
	s_mov_b64 s[24:25], -1
	v_sub_f32_e32 v70, v70, v71
	v_add_f32_e32 v66, v66, v67
	v_cvt_pk_bf16_f32 v89, v70, v66

.LBB0_583:
	s_and_b64 vcc, exec, s[36:37]
	s_cbranch_vccz .LBB0_598
	v_lshlrev_b64 v[66:67], 8, v[78:79]
	v_lshl_add_u64 v[70:71], v[158:159], 0, v[66:67]
	s_nop 0
	s_mov_b64 s[24:25], -1
	s_andn2_b64 vcc, exec, s[46:47]
	v_mov_b64_e32 v[66:67], v[218:219]
	v_mov_b64_e32 v[68:69], v[220:221]
	v_mov_b64_e32 v[70:71], v[214:215]
	v_mov_b64_e32 v[72:73], v[216:217]
	v_pk_mul_f32 v[74:75], v[62:63], v[70:71]
	v_pk_mul_f32 v[76:77], v[64:65], v[72:73]
	v_sub_f32_e32 v80, v74, v75
	v_pk_mul_f32 v[74:75], v[62:63], v[70:71] op_sel:[1,0] op_sel_hi:[0,1]
	v_add_f32_e32 v74, v74, v75
	v_sub_f32_e32 v75, v76, v77
	v_pk_mul_f32 v[76:77], v[64:65], v[72:73] op_sel:[1,0] op_sel_hi:[0,1]
	v_add_f32_e32 v76, v76, v77
	v_cvt_pk_bf16_f32 v74, v80, v74
	v_cvt_pk_bf16_f32 v75, v75, v76
	v_pk_mul_f32 v[76:77], v[58:59], v[66:67]
	v_pk_mul_f32 v[80:81], v[60:61], v[68:69]
	v_sub_f32_e32 v82, v76, v77
	v_pk_mul_f32 v[76:77], v[58:59], v[66:67] op_sel:[1,0] op_sel_hi:[0,1]
	v_add_f32_e32 v76, v76, v77
	v_sub_f32_e32 v77, v80, v81
	v_pk_mul_f32 v[80:81], v[60:61], v[68:69] op_sel:[1,0] op_sel_hi:[0,1]
	v_cvt_pk_bf16_f32 v76, v82, v76
	v_add_f32_e32 v80, v80, v81
	v_cvt_pk_bf16_f32 v77, v77, v80
	s_cbranch_vccnz .LBB0_592
	v_readlane_b32 s24, v255, 17
	v_readlane_b32 s25, v255, 18
	s_andn2_b64 vcc, exec, s[24:25]
	s_mov_b64 s[24:25], -1
	s_cbranch_vccnz .LBB0_589
	s_and_saveexec_b64 s[24:25], s[84:85]
	s_cbranch_execz .LBB0_588
	v_readlane_b32 s34, v255, 1
	v_lshlrev_b64 v[80:81], 4, v[78:79]
	v_readlane_b32 s35, v255, 2
	s_nop 1
	v_lshl_add_u64 v[80:81], v[80:81], 2, s[34:35]
	s_mov_b32 s34, 0x3d000000
	v_lshl_add_u64 v[88:89], v[154:155], 2, v[80:81]
	v_pk_mul_f32 v[86:87], v[64:65], s[34:35] op_sel_hi:[1,0]
	v_pk_mul_f32 v[84:85], v[62:63], s[34:35] op_sel_hi:[1,0]
	v_pk_mul_f32 v[82:83], v[60:61], s[34:35] op_sel_hi:[1,0]
	v_pk_mul_f32 v[80:81], v[58:59], s[34:35] op_sel_hi:[1,0]
	global_store_dwordx4 v[88:89], v[84:87], off
	global_store_dwordx4 v[88:89], v[80:83], off offset:16

.LBB0_602:
	v_lshlrev_b64 v[66:67], 9, v[78:79]
	v_lshl_add_u64 v[70:71], v[140:141], 0, v[66:67]
	s_nop 0
	s_and_b64 vcc, exec, s[8:9]
	s_mov_b64 s[24:25], -1
	s_cbranch_vccnz .LBB0_604
	v_lshlrev_b64 v[74:75], 10, v[78:79]
	v_lshl_add_u64 v[74:75], s[22:23], 0, v[74:75]
	v_lshl_add_u64 v[74:75], s[50:51], 1, v[74:75]
	s_mov_b64 s[24:25], 0x2e5ff000
	v_lshl_add_u64 v[74:75], v[74:75], 0, s[24:25]
	s_mov_b64 s[24:25], 0

.LBB0_606:
	v_mov_b32_e32 v76, v138
	v_mov_b32_e32 v77, v138
	v_pk_mul_f32 v[62:63], v[138:139], v[62:63]
	v_pk_mul_f32 v[64:65], v[76:77], v[64:65]
	v_pk_mul_f32 v[78:79], v[76:77], v[60:61]
	v_pk_mul_f32 v[60:61], v[138:139], v[58:59]
	v_mov_b64_e32 v[66:67], v[218:219]
	v_mov_b64_e32 v[68:69], v[220:221]
	v_mov_b64_e32 v[70:71], v[214:215]
	v_mov_b64_e32 v[72:73], v[216:217]
	v_pk_mul_f32 v[58:59], v[62:63], v[70:71]
	v_pk_mul_f32 v[80:81], v[64:65], v[72:73]
	v_sub_f32_e32 v82, v58, v59
	v_pk_mul_f32 v[58:59], v[62:63], v[70:71] op_sel:[1,0] op_sel_hi:[0,1]
	v_pk_mul_f32 v[62:63], v[64:65], v[72:73] op_sel:[1,0] op_sel_hi:[0,1]
	v_add_f32_e32 v58, v58, v59
	v_sub_f32_e32 v59, v80, v81
	v_add_f32_e32 v62, v62, v63
	v_cvt_pk_bf16_f32 v58, v82, v58
	v_cvt_pk_bf16_f32 v59, v59, v62
	v_pk_mul_f32 v[62:63], v[78:79], v[68:69]
	v_pk_mul_f32 v[64:65], v[60:61], v[66:67]
	v_pk_mul_f32 v[60:61], v[60:61], v[66:67] op_sel:[1,0] op_sel_hi:[0,1]
	v_add_f32_e32 v60, v60, v61
	v_sub_f32_e32 v61, v62, v63
	v_pk_mul_f32 v[62:63], v[78:79], v[68:69] op_sel:[1,0] op_sel_hi:[0,1]
	v_lshl_add_u64 v[74:75], v[152:153], 1, v[74:75]
	v_sub_f32_e32 v64, v64, v65
	v_cvt_pk_bf16_f32 v60, v64, v60
	v_add_f32_e32 v62, v62, v63
	v_cvt_pk_bf16_f32 v61, v61, v62
	v_pk_mul_f32 v[54:55], v[138:139], v[54:55]
	global_store_dwordx4 v[74:75], v[58:61], off
	v_pk_mul_f32 v[56:57], v[76:77], v[56:57]
	v_pk_mul_f32 v[50:51], v[138:139], v[50:51]
	v_pk_mul_f32 v[60:61], v[54:55], v[70:71]
	v_pk_mul_f32 v[54:55], v[54:55], v[70:71] op_sel:[1,0] op_sel_hi:[0,1]
	v_add_f32_e32 v54, v54, v55
	v_pk_mul_f32 v[58:59], v[56:57], v[72:73]
	v_sub_f32_e32 v60, v60, v61
	v_cvt_pk_bf16_f32 v70, v60, v54
	v_pk_mul_f32 v[54:55], v[56:57], v[72:73] op_sel:[1,0] op_sel_hi:[0,1]
	v_pk_mul_f32 v[56:57], v[50:51], v[66:67]
	v_pk_mul_f32 v[50:51], v[50:51], v[66:67] op_sel:[1,0] op_sel_hi:[0,1]
	v_pk_mul_f32 v[52:53], v[76:77], v[52:53]
	v_add_f32_e32 v54, v54, v55
	v_add_f32_e32 v50, v50, v51
	s_mov_b64 s[24:25], 0x100
	v_sub_f32_e32 v58, v58, v59
	v_cvt_pk_bf16_f32 v71, v58, v54
	v_pk_mul_f32 v[54:55], v[52:53], v[68:69]
	v_sub_f32_e32 v56, v56, v57
	v_cvt_pk_bf16_f32 v72, v56, v50
	v_pk_mul_f32 v[50:51], v[52:53], v[68:69] op_sel:[1,0] op_sel_hi:[0,1]
	v_lshl_add_u64 v[66:67], v[74:75], 0, s[24:25]
	s_mov_b64 s[24:25], -1
	v_sub_f32_e32 v54, v54, v55
	v_add_f32_e32 v50, v50, v51
	v_cvt_pk_bf16_f32 v73, v54, v50

.LBB0_609:
	s_and_b64 vcc, exec, s[36:37]
	s_cbranch_vccz .LBB0_624
	v_lshlrev_b64 v[50:51], 8, v[62:63]
	v_lshl_add_u64 v[50:51], v[158:159], 0, v[50:51]
	s_nop 0
	s_andn2_b64 vcc, exec, s[46:47]
	s_mov_b64 s[24:25], -1
	v_mov_b64_e32 v[54:55], v[222:223]
	v_mov_b64_e32 v[56:57], v[224:225]
	v_mov_b64_e32 v[50:51], v[226:227]
	v_mov_b64_e32 v[52:53], v[228:229]
	v_pk_mul_f32 v[58:59], v[48:49], v[56:57]
	v_pk_mul_f32 v[60:61], v[46:47], v[54:55]
	v_pk_mul_f32 v[64:65], v[46:47], v[54:55] op_sel:[1,0] op_sel_hi:[0,1]
	v_pk_mul_f32 v[66:67], v[48:49], v[56:57] op_sel:[1,0] op_sel_hi:[0,1]
	v_pk_mul_f32 v[68:69], v[44:45], v[52:53]
	v_pk_mul_f32 v[70:71], v[42:43], v[50:51]
	v_pk_mul_f32 v[72:73], v[42:43], v[50:51] op_sel:[1,0] op_sel_hi:[0,1]
	v_pk_mul_f32 v[74:75], v[44:45], v[52:53] op_sel:[1,0] op_sel_hi:[0,1]
	v_sub_f32_e32 v60, v60, v61
	v_add_f32_e32 v61, v64, v65
	v_sub_f32_e32 v59, v58, v59
	v_add_f32_e32 v64, v66, v67
	v_sub_f32_e32 v65, v70, v71
	v_add_f32_e32 v66, v72, v73
	v_sub_f32_e32 v67, v68, v69
	v_add_f32_e32 v68, v74, v75
	v_cvt_pk_bf16_f32 v58, v60, v61
	v_cvt_pk_bf16_f32 v59, v59, v64
	v_cvt_pk_bf16_f32 v60, v65, v66
	v_cvt_pk_bf16_f32 v61, v67, v68
	s_cbranch_vccnz .LBB0_618
	v_readlane_b32 s24, v255, 17
	v_readlane_b32 s25, v255, 18
	s_andn2_b64 vcc, exec, s[24:25]
	s_mov_b64 s[24:25], -1
	s_cbranch_vccnz .LBB0_615
	s_and_saveexec_b64 s[24:25], s[84:85]
	s_cbranch_execz .LBB0_614
	v_readlane_b32 s34, v255, 1
	v_lshlrev_b64 v[64:65], 4, v[62:63]
	v_readlane_b32 s35, v255, 2
	s_nop 1
	v_lshl_add_u64 v[64:65], v[64:65], 2, s[34:35]
	s_mov_b32 s34, 0x3d000000
	v_lshl_add_u64 v[72:73], v[154:155], 2, v[64:65]
	v_pk_mul_f32 v[70:71], v[48:49], s[34:35] op_sel_hi:[1,0]
	v_pk_mul_f32 v[68:69], v[46:47], s[34:35] op_sel_hi:[1,0]
	v_pk_mul_f32 v[66:67], v[44:45], s[34:35] op_sel_hi:[1,0]
	v_pk_mul_f32 v[64:65], v[42:43], s[34:35] op_sel_hi:[1,0]
	global_store_dwordx4 v[72:73], v[68:71], off
	global_store_dwordx4 v[72:73], v[64:67], off offset:16

.LBB0_628:
	v_lshlrev_b64 v[50:51], 9, v[62:63]
	v_lshl_add_u64 v[54:55], v[140:141], 0, v[50:51]
	s_nop 0
	s_and_b64 vcc, exec, s[8:9]
	s_mov_b64 s[24:25], -1
	s_cbranch_vccnz .LBB0_630
	v_lshlrev_b64 v[58:59], 10, v[62:63]
	v_lshl_add_u64 v[58:59], s[22:23], 0, v[58:59]
	v_lshl_add_u64 v[58:59], s[50:51], 1, v[58:59]
	s_mov_b64 s[24:25], 0x2e5ff000
	v_lshl_add_u64 v[58:59], v[58:59], 0, s[24:25]
	s_mov_b64 s[24:25], 0

.LBB0_632:
	v_mov_b32_e32 v60, v138
	v_mov_b32_e32 v61, v138
	v_pk_mul_f32 v[46:47], v[138:139], v[46:47]
	v_pk_mul_f32 v[48:49], v[60:61], v[48:49]
	v_pk_mul_f32 v[62:63], v[60:61], v[44:45]
	v_pk_mul_f32 v[44:45], v[138:139], v[42:43]
	v_mov_b64_e32 v[50:51], v[226:227]
	v_mov_b64_e32 v[52:53], v[228:229]
	v_mov_b64_e32 v[54:55], v[222:223]
	v_mov_b64_e32 v[56:57], v[224:225]
	v_pk_mul_f32 v[42:43], v[46:47], v[54:55]
	v_pk_mul_f32 v[64:65], v[48:49], v[56:57]
	v_sub_f32_e32 v66, v42, v43
	v_pk_mul_f32 v[42:43], v[46:47], v[54:55] op_sel:[1,0] op_sel_hi:[0,1]
	v_pk_mul_f32 v[46:47], v[48:49], v[56:57] op_sel:[1,0] op_sel_hi:[0,1]
	v_add_f32_e32 v42, v42, v43
	v_sub_f32_e32 v43, v64, v65
	v_add_f32_e32 v46, v46, v47
	v_cvt_pk_bf16_f32 v42, v66, v42
	v_cvt_pk_bf16_f32 v43, v43, v46
	v_pk_mul_f32 v[46:47], v[62:63], v[52:53]
	v_pk_mul_f32 v[48:49], v[44:45], v[50:51]
	v_pk_mul_f32 v[44:45], v[44:45], v[50:51] op_sel:[1,0] op_sel_hi:[0,1]
	v_add_f32_e32 v44, v44, v45
	v_sub_f32_e32 v45, v46, v47
	v_pk_mul_f32 v[46:47], v[62:63], v[52:53] op_sel:[1,0] op_sel_hi:[0,1]
	v_lshl_add_u64 v[58:59], v[152:153], 1, v[58:59]
	v_sub_f32_e32 v48, v48, v49
	v_cvt_pk_bf16_f32 v44, v48, v44
	v_add_f32_e32 v46, v46, v47
	v_cvt_pk_bf16_f32 v45, v45, v46
	v_pk_mul_f32 v[38:39], v[138:139], v[38:39]
	global_store_dwordx4 v[58:59], v[42:45], off
	v_pk_mul_f32 v[40:41], v[60:61], v[40:41]
	v_pk_mul_f32 v[34:35], v[138:139], v[34:35]
	v_pk_mul_f32 v[44:45], v[38:39], v[54:55]
	v_pk_mul_f32 v[38:39], v[38:39], v[54:55] op_sel:[1,0] op_sel_hi:[0,1]
	v_add_f32_e32 v38, v38, v39
	v_pk_mul_f32 v[42:43], v[40:41], v[56:57]
	v_sub_f32_e32 v44, v44, v45
	v_cvt_pk_bf16_f32 v54, v44, v38
	v_pk_mul_f32 v[38:39], v[40:41], v[56:57] op_sel:[1,0] op_sel_hi:[0,1]
	v_pk_mul_f32 v[40:41], v[34:35], v[50:51]
	v_pk_mul_f32 v[34:35], v[34:35], v[50:51] op_sel:[1,0] op_sel_hi:[0,1]
	v_pk_mul_f32 v[36:37], v[60:61], v[36:37]
	v_add_f32_e32 v38, v38, v39
	v_add_f32_e32 v34, v34, v35
	s_mov_b64 s[24:25], 0x100
	v_sub_f32_e32 v42, v42, v43
	v_cvt_pk_bf16_f32 v55, v42, v38
	v_pk_mul_f32 v[38:39], v[36:37], v[52:53]
	v_sub_f32_e32 v40, v40, v41
	v_cvt_pk_bf16_f32 v56, v40, v34
	v_pk_mul_f32 v[34:35], v[36:37], v[52:53] op_sel:[1,0] op_sel_hi:[0,1]
	v_lshl_add_u64 v[50:51], v[58:59], 0, s[24:25]
	s_mov_b64 s[24:25], -1
	v_sub_f32_e32 v38, v38, v39
	v_add_f32_e32 v34, v34, v35
	v_cvt_pk_bf16_f32 v57, v38, v34

.LBB0_635:
	s_and_b64 vcc, exec, s[36:37]
	s_cbranch_vccz .LBB0_650
	v_lshlrev_b64 v[34:35], 8, v[46:47]
	v_lshl_add_u64 v[38:39], v[158:159], 0, v[34:35]
	s_nop 0
	s_mov_b64 s[24:25], -1
	s_andn2_b64 vcc, exec, s[46:47]
	v_mov_b64_e32 v[34:35], v[236:237]
	v_mov_b64_e32 v[36:37], v[238:239]
	v_mov_b64_e32 v[38:39], v[232:233]
	v_mov_b64_e32 v[40:41], v[234:235]
	v_pk_mul_f32 v[42:43], v[30:31], v[38:39]
	v_pk_mul_f32 v[44:45], v[32:33], v[40:41]
	v_sub_f32_e32 v48, v42, v43
	v_pk_mul_f32 v[42:43], v[30:31], v[38:39] op_sel:[1,0] op_sel_hi:[0,1]
	v_add_f32_e32 v42, v42, v43
	v_sub_f32_e32 v43, v44, v45
	v_pk_mul_f32 v[44:45], v[32:33], v[40:41] op_sel:[1,0] op_sel_hi:[0,1]
	v_add_f32_e32 v44, v44, v45
	v_cvt_pk_bf16_f32 v42, v48, v42
	v_cvt_pk_bf16_f32 v43, v43, v44
	v_pk_mul_f32 v[44:45], v[26:27], v[34:35]
	v_pk_mul_f32 v[48:49], v[28:29], v[36:37]
	v_sub_f32_e32 v50, v44, v45
	v_pk_mul_f32 v[44:45], v[26:27], v[34:35] op_sel:[1,0] op_sel_hi:[0,1]
	v_add_f32_e32 v44, v44, v45
	v_sub_f32_e32 v45, v48, v49
	v_pk_mul_f32 v[48:49], v[28:29], v[36:37] op_sel:[1,0] op_sel_hi:[0,1]
	v_cvt_pk_bf16_f32 v44, v50, v44
	v_add_f32_e32 v48, v48, v49
	v_cvt_pk_bf16_f32 v45, v45, v48
	s_cbranch_vccnz .LBB0_644
	v_readlane_b32 s24, v255, 17
	v_readlane_b32 s25, v255, 18
	s_andn2_b64 vcc, exec, s[24:25]
	s_mov_b64 s[24:25], -1
	s_cbranch_vccnz .LBB0_641
	s_and_saveexec_b64 s[24:25], s[84:85]
	s_cbranch_execz .LBB0_640
	v_readlane_b32 s34, v255, 1
	v_lshlrev_b64 v[48:49], 4, v[46:47]
	v_readlane_b32 s35, v255, 2
	s_nop 1
	v_lshl_add_u64 v[48:49], v[48:49], 2, s[34:35]
	s_mov_b32 s34, 0x3d000000
	v_lshl_add_u64 v[56:57], v[154:155], 2, v[48:49]
	v_pk_mul_f32 v[54:55], v[32:33], s[34:35] op_sel_hi:[1,0]
	v_pk_mul_f32 v[52:53], v[30:31], s[34:35] op_sel_hi:[1,0]
	v_pk_mul_f32 v[50:51], v[28:29], s[34:35] op_sel_hi:[1,0]
	v_pk_mul_f32 v[48:49], v[26:27], s[34:35] op_sel_hi:[1,0]
	global_store_dwordx4 v[56:57], v[52:55], off
	global_store_dwordx4 v[56:57], v[48:51], off offset:16

.LBB0_654:
	v_lshlrev_b64 v[34:35], 9, v[46:47]
	v_lshl_add_u64 v[38:39], v[140:141], 0, v[34:35]
	s_nop 0
	s_and_b64 vcc, exec, s[8:9]
	s_mov_b64 s[24:25], -1
	s_cbranch_vccnz .LBB0_656
	v_lshlrev_b64 v[42:43], 10, v[46:47]
	v_lshl_add_u64 v[42:43], s[22:23], 0, v[42:43]
	v_lshl_add_u64 v[42:43], s[50:51], 1, v[42:43]
	s_mov_b64 s[24:25], 0x2e5ff000
	v_lshl_add_u64 v[42:43], v[42:43], 0, s[24:25]
	s_mov_b64 s[24:25], 0

.LBB0_658:
	v_mov_b32_e32 v44, v138
	v_mov_b32_e32 v45, v138
	v_pk_mul_f32 v[30:31], v[138:139], v[30:31]
	v_pk_mul_f32 v[32:33], v[44:45], v[32:33]
	v_pk_mul_f32 v[46:47], v[44:45], v[28:29]
	v_pk_mul_f32 v[28:29], v[138:139], v[26:27]
	v_mov_b64_e32 v[34:35], v[236:237]
	v_mov_b64_e32 v[36:37], v[238:239]
	v_mov_b64_e32 v[38:39], v[232:233]
	v_mov_b64_e32 v[40:41], v[234:235]
	v_pk_mul_f32 v[26:27], v[30:31], v[38:39]
	v_pk_mul_f32 v[48:49], v[32:33], v[40:41]
	v_sub_f32_e32 v50, v26, v27
	v_pk_mul_f32 v[26:27], v[30:31], v[38:39] op_sel:[1,0] op_sel_hi:[0,1]
	v_pk_mul_f32 v[30:31], v[32:33], v[40:41] op_sel:[1,0] op_sel_hi:[0,1]
	v_add_f32_e32 v26, v26, v27
	v_sub_f32_e32 v27, v48, v49
	v_add_f32_e32 v30, v30, v31
	v_cvt_pk_bf16_f32 v26, v50, v26
	v_cvt_pk_bf16_f32 v27, v27, v30
	v_pk_mul_f32 v[30:31], v[46:47], v[36:37]
	v_pk_mul_f32 v[32:33], v[28:29], v[34:35]
	v_pk_mul_f32 v[28:29], v[28:29], v[34:35] op_sel:[1,0] op_sel_hi:[0,1]
	v_add_f32_e32 v28, v28, v29
	v_sub_f32_e32 v29, v30, v31
	v_pk_mul_f32 v[30:31], v[46:47], v[36:37] op_sel:[1,0] op_sel_hi:[0,1]
	v_lshl_add_u64 v[42:43], v[152:153], 1, v[42:43]
	v_sub_f32_e32 v32, v32, v33
	v_cvt_pk_bf16_f32 v28, v32, v28
	v_add_f32_e32 v30, v30, v31
	v_cvt_pk_bf16_f32 v29, v29, v30
	v_pk_mul_f32 v[22:23], v[138:139], v[22:23]
	global_store_dwordx4 v[42:43], v[26:29], off
	v_pk_mul_f32 v[24:25], v[44:45], v[24:25]
	v_pk_mul_f32 v[18:19], v[138:139], v[18:19]
	v_pk_mul_f32 v[28:29], v[22:23], v[38:39]
	v_pk_mul_f32 v[22:23], v[22:23], v[38:39] op_sel:[1,0] op_sel_hi:[0,1]
	v_add_f32_e32 v22, v22, v23
	v_pk_mul_f32 v[26:27], v[24:25], v[40:41]
	v_sub_f32_e32 v28, v28, v29
	v_cvt_pk_bf16_f32 v38, v28, v22
	v_pk_mul_f32 v[22:23], v[24:25], v[40:41] op_sel:[1,0] op_sel_hi:[0,1]
	v_pk_mul_f32 v[24:25], v[18:19], v[34:35]
	v_pk_mul_f32 v[18:19], v[18:19], v[34:35] op_sel:[1,0] op_sel_hi:[0,1]
	v_pk_mul_f32 v[20:21], v[44:45], v[20:21]
	v_add_f32_e32 v22, v22, v23
	v_add_f32_e32 v18, v18, v19
	s_mov_b64 s[24:25], 0x100
	v_sub_f32_e32 v26, v26, v27
	v_cvt_pk_bf16_f32 v39, v26, v22
	v_pk_mul_f32 v[22:23], v[20:21], v[36:37]
	v_sub_f32_e32 v24, v24, v25
	v_cvt_pk_bf16_f32 v40, v24, v18
	v_pk_mul_f32 v[18:19], v[20:21], v[36:37] op_sel:[1,0] op_sel_hi:[0,1]
	v_lshl_add_u64 v[34:35], v[42:43], 0, s[24:25]
	s_mov_b64 s[24:25], -1
	v_sub_f32_e32 v22, v22, v23
	v_add_f32_e32 v18, v18, v19
	v_cvt_pk_bf16_f32 v41, v22, v18

.LBB0_661:
	s_and_b64 vcc, exec, s[36:37]
	s_cbranch_vccz .LBB0_676
	v_lshlrev_b64 v[18:19], 8, v[30:31]
	v_lshl_add_u64 v[22:23], v[158:159], 0, v[18:19]
	s_nop 0
	s_mov_b64 s[10:11], -1
	s_andn2_b64 vcc, exec, s[46:47]
	v_mov_b64_e32 v[18:19], v[248:249]
	v_mov_b64_e32 v[20:21], v[250:251]
	v_mov_b64_e32 v[22:23], v[240:241]
	v_mov_b64_e32 v[24:25], v[242:243]
	v_pk_mul_f32 v[26:27], v[14:15], v[22:23]
	v_pk_mul_f32 v[28:29], v[16:17], v[24:25]
	v_sub_f32_e32 v32, v26, v27
	v_pk_mul_f32 v[26:27], v[14:15], v[22:23] op_sel:[1,0] op_sel_hi:[0,1]
	v_add_f32_e32 v26, v26, v27
	v_sub_f32_e32 v27, v28, v29
	v_pk_mul_f32 v[28:29], v[16:17], v[24:25] op_sel:[1,0] op_sel_hi:[0,1]
	v_add_f32_e32 v28, v28, v29
	v_cvt_pk_bf16_f32 v26, v32, v26
	v_cvt_pk_bf16_f32 v27, v27, v28
	v_pk_mul_f32 v[28:29], v[10:11], v[18:19]
	v_pk_mul_f32 v[32:33], v[12:13], v[20:21]
	v_sub_f32_e32 v34, v28, v29
	v_pk_mul_f32 v[28:29], v[10:11], v[18:19] op_sel:[1,0] op_sel_hi:[0,1]
	v_add_f32_e32 v28, v28, v29
	v_sub_f32_e32 v29, v32, v33
	v_pk_mul_f32 v[32:33], v[12:13], v[20:21] op_sel:[1,0] op_sel_hi:[0,1]
	v_cvt_pk_bf16_f32 v28, v34, v28
	v_add_f32_e32 v32, v32, v33
	v_cvt_pk_bf16_f32 v29, v29, v32
	s_cbranch_vccnz .LBB0_670
	v_readlane_b32 s10, v255, 17
	v_readlane_b32 s11, v255, 18
	s_andn2_b64 vcc, exec, s[10:11]
	s_mov_b64 s[10:11], -1
	s_cbranch_vccnz .LBB0_667
	s_and_saveexec_b64 s[10:11], s[84:85]
	s_cbranch_execz .LBB0_666
	v_readlane_b32 s24, v255, 1
	v_lshlrev_b64 v[32:33], 4, v[30:31]
	v_readlane_b32 s25, v255, 2
	s_nop 1
	v_lshl_add_u64 v[32:33], v[32:33], 2, s[24:25]
	s_mov_b32 s24, 0x3d000000
	v_lshl_add_u64 v[40:41], v[154:155], 2, v[32:33]
	v_pk_mul_f32 v[38:39], v[16:17], s[24:25] op_sel_hi:[1,0]
	v_pk_mul_f32 v[36:37], v[14:15], s[24:25] op_sel_hi:[1,0]
	v_pk_mul_f32 v[34:35], v[12:13], s[24:25] op_sel_hi:[1,0]
	v_pk_mul_f32 v[32:33], v[10:11], s[24:25] op_sel_hi:[1,0]
	global_store_dwordx4 v[40:41], v[36:39], off
	global_store_dwordx4 v[40:41], v[32:35], off offset:16

.LBB0_680:
	v_lshlrev_b64 v[18:19], 9, v[30:31]
	v_lshl_add_u64 v[22:23], v[140:141], 0, v[18:19]
	s_nop 0
	s_and_b64 vcc, exec, s[8:9]
	s_mov_b64 s[8:9], -1
	s_cbranch_vccnz .LBB0_682
	v_lshlrev_b64 v[26:27], 10, v[30:31]
	v_lshl_add_u64 v[26:27], s[22:23], 0, v[26:27]
	v_lshl_add_u64 v[26:27], s[50:51], 1, v[26:27]
	s_mov_b64 s[8:9], 0x2e5ff000
	v_lshl_add_u64 v[26:27], v[26:27], 0, s[8:9]
	s_mov_b64 s[8:9], 0

.LBB0_684:
	v_mov_b32_e32 v28, v138
	v_mov_b32_e32 v29, v138
	v_pk_mul_f32 v[14:15], v[138:139], v[14:15]
	v_pk_mul_f32 v[16:17], v[28:29], v[16:17]
	v_pk_mul_f32 v[30:31], v[28:29], v[12:13]
	v_pk_mul_f32 v[12:13], v[138:139], v[10:11]
	v_mov_b64_e32 v[18:19], v[248:249]
	v_mov_b64_e32 v[20:21], v[250:251]
	v_mov_b64_e32 v[22:23], v[240:241]
	v_mov_b64_e32 v[24:25], v[242:243]
	v_pk_mul_f32 v[10:11], v[14:15], v[22:23]
	v_pk_mul_f32 v[32:33], v[16:17], v[24:25]
	v_sub_f32_e32 v34, v10, v11
	v_pk_mul_f32 v[10:11], v[14:15], v[22:23] op_sel:[1,0] op_sel_hi:[0,1]
	v_pk_mul_f32 v[14:15], v[16:17], v[24:25] op_sel:[1,0] op_sel_hi:[0,1]
	v_add_f32_e32 v10, v10, v11
	v_sub_f32_e32 v11, v32, v33
	v_add_f32_e32 v14, v14, v15
	v_cvt_pk_bf16_f32 v10, v34, v10
	v_cvt_pk_bf16_f32 v11, v11, v14
	v_pk_mul_f32 v[14:15], v[30:31], v[20:21]
	v_pk_mul_f32 v[16:17], v[12:13], v[18:19]
	v_pk_mul_f32 v[12:13], v[12:13], v[18:19] op_sel:[1,0] op_sel_hi:[0,1]
	v_add_f32_e32 v12, v12, v13
	v_sub_f32_e32 v13, v14, v15
	v_pk_mul_f32 v[14:15], v[30:31], v[20:21] op_sel:[1,0] op_sel_hi:[0,1]
	v_lshl_add_u64 v[26:27], v[152:153], 1, v[26:27]
	v_sub_f32_e32 v16, v16, v17
	v_cvt_pk_bf16_f32 v12, v16, v12
	v_add_f32_e32 v14, v14, v15
	v_cvt_pk_bf16_f32 v13, v13, v14
	v_pk_mul_f32 v[6:7], v[138:139], v[6:7]
	global_store_dwordx4 v[26:27], v[10:13], off
	v_pk_mul_f32 v[8:9], v[28:29], v[8:9]
	v_pk_mul_f32 v[2:3], v[138:139], v[2:3]
	v_pk_mul_f32 v[12:13], v[6:7], v[22:23]
	v_pk_mul_f32 v[6:7], v[6:7], v[22:23] op_sel:[1,0] op_sel_hi:[0,1]
	v_add_f32_e32 v6, v6, v7
	v_pk_mul_f32 v[10:11], v[8:9], v[24:25]
	v_sub_f32_e32 v12, v12, v13
	v_cvt_pk_bf16_f32 v22, v12, v6
	v_pk_mul_f32 v[6:7], v[8:9], v[24:25] op_sel:[1,0] op_sel_hi:[0,1]
	v_pk_mul_f32 v[8:9], v[2:3], v[18:19]
	v_pk_mul_f32 v[2:3], v[2:3], v[18:19] op_sel:[1,0] op_sel_hi:[0,1]
	v_pk_mul_f32 v[4:5], v[28:29], v[4:5]
	v_add_f32_e32 v6, v6, v7
	v_add_f32_e32 v2, v2, v3
	s_mov_b64 s[0:1], 0x100
	v_sub_f32_e32 v10, v10, v11
	v_cvt_pk_bf16_f32 v23, v10, v6
	v_pk_mul_f32 v[6:7], v[4:5], v[20:21]
	v_sub_f32_e32 v8, v8, v9
	v_cvt_pk_bf16_f32 v24, v8, v2
	v_pk_mul_f32 v[2:3], v[4:5], v[20:21] op_sel:[1,0] op_sel_hi:[0,1]
	v_lshl_add_u64 v[18:19], v[26:27], 0, s[0:1]
	s_mov_b64 s[10:11], -1
	v_sub_f32_e32 v6, v6, v7
	v_add_f32_e32 v2, v2, v3
	v_cvt_pk_bf16_f32 v25, v6, v2

	.amdhsa_kernel _Z14fwd_megakernel4Args
		.amdhsa_group_segment_fixed_size 0
		.amdhsa_private_segment_fixed_size 0
		.amdhsa_kernarg_size 376
		.amdhsa_user_sgpr_count 2
		.amdhsa_user_sgpr_dispatch_ptr 0
		.amdhsa_user_sgpr_queue_ptr 0
		.amdhsa_user_sgpr_kernarg_segment_ptr 1
		.amdhsa_user_sgpr_dispatch_id 0
		.amdhsa_user_sgpr_kernarg_preload_length 0
		.amdhsa_user_sgpr_kernarg_preload_offset 0
		.amdhsa_user_sgpr_private_segment_size 0
		.amdhsa_uses_dynamic_stack 0
		.amdhsa_enable_private_segment 0
		.amdhsa_system_sgpr_workgroup_id_x 1
		.amdhsa_system_sgpr_workgroup_id_y 0
		.amdhsa_system_sgpr_workgroup_id_z 0
		.amdhsa_system_sgpr_workgroup_info 0
		.amdhsa_system_vgpr_workitem_id 2
		.amdhsa_next_free_vgpr 256
		.amdhsa_next_free_sgpr 102
		.amdhsa_accum_offset 256
		.amdhsa_reserve_vcc 1
		.amdhsa_float_round_mode_32 0
		.amdhsa_float_round_mode_16_64 0
		.amdhsa_float_denorm_mode_32 3
		.amdhsa_float_denorm_mode_16_64 3
		.amdhsa_dx10_clamp 1
		.amdhsa_ieee_mode 1
		.amdhsa_fp16_overflow 0
		.amdhsa_tg_split 0
		.amdhsa_exception_fp_ieee_invalid_op 0
		.amdhsa_exception_fp_denorm_src 0
		.amdhsa_exception_fp_ieee_div_zero 0
		.amdhsa_exception_fp_ieee_overflow 0
		.amdhsa_exception_fp_ieee_underflow 0
		.amdhsa_exception_fp_ieee_inexact 0
		.amdhsa_exception_int_div_zero 0
	.end_amdhsa_kernel

amdhsa.kernels:
  - .agpr_count:     0
    .args:
      - .offset:         0
        .size:           120
        .value_kind:     by_value
      - .offset:         120
        .size:           4
        .value_kind:     hidden_block_count_x
      - .offset:         124
        .size:           4
        .value_kind:     hidden_block_count_y
      - .offset:         128
        .size:           4
        .value_kind:     hidden_block_count_z
      - .offset:         132
        .size:           2
        .value_kind:     hidden_group_size_x
      - .offset:         134
        .size:           2
        .value_kind:     hidden_group_size_y
      - .offset:         136
        .size:           2
        .value_kind:     hidden_group_size_z
      - .offset:         138
        .size:           2
        .value_kind:     hidden_remainder_x
      - .offset:         140
        .size:           2
        .value_kind:     hidden_remainder_y
      - .offset:         142
        .size:           2
        .value_kind:     hidden_remainder_z
      - .offset:         160
        .size:           8
        .value_kind:     hidden_global_offset_x
      - .offset:         168
        .size:           8
        .value_kind:     hidden_global_offset_y
      - .offset:         176
        .size:           8
        .value_kind:     hidden_global_offset_z
      - .offset:         184
        .size:           2
        .value_kind:     hidden_grid_dims
      - .offset:         208
        .size:           8
        .value_kind:     hidden_multigrid_sync_arg
      - .offset:         240
        .size:           4
        .value_kind:     hidden_dynamic_lds_size
    .group_segment_fixed_size: 0
    .kernarg_segment_align: 8
    .kernarg_segment_size: 376
    .language:       OpenCL C
    .language_version:
      - 2
      - 0
    .max_flat_workgroup_size: 512
    .name:           _Z14fwd_megakernel4Args
    .private_segment_fixed_size: 0
    .sgpr_count:     108
    .sgpr_spill_count: 286
    .symbol:         _Z14fwd_megakernel4Args.kd
    .uniform_work_group_size: 1
    .uses_dynamic_stack: false
    .vgpr_count:     256
    .vgpr_spill_count: 0
    .wavefront_size: 64
